# add transposed row-sum-of-squares stats layout (contiguous 64B write-through stores instead of 16 scattered dwords)
# speedup vs baseline: 1.0208x; 1.0153x over previous
.LBB0_632:
	v_mul_f32_e32 v151, v125, v125
	v_mul_f32_e32 v154, v127, v127
	v_fmac_f32_e32 v151, v124, v124
	v_fmac_f32_e32 v154, v126, v126
	v_add_f32_e32 v151, v151, v154
	v_mul_f32_e32 v154, v121, v121
	v_fmac_f32_e32 v154, v120, v120
	v_cvt_pk_bf16_f32 v124, v124, v125
	v_cvt_pk_bf16_f32 v125, v126, v127
	v_cvt_pk_bf16_f32 v126, v120, v121
	v_mul_f32_e32 v120, v117, v117
	v_mul_f32_e32 v121, v119, v119
	v_fmac_f32_e32 v120, v116, v116
	v_fmac_f32_e32 v121, v118, v118
	v_add_f32_e32 v120, v120, v121
	v_mul_f32_e32 v121, v113, v113
	v_fmac_f32_e32 v121, v112, v112
	v_add_f32_e32 v151, v151, v154
	v_mul_f32_e32 v154, v123, v123
	v_add_f32_e32 v120, v120, v121
	v_mul_f32_e32 v121, v115, v115
	v_fmac_f32_e32 v154, v122, v122
	v_fmac_f32_e32 v121, v114, v114
	v_add_f32_e32 v151, v154, v151
	v_add_f32_e32 v120, v121, v120
	v_lshl_add_u32 v144, s10, 8, v146
	v_add_f32_e32 v120, v151, v120
	v_ashrrev_i32_e32 v145, 31, v144
	ds_bpermute_b32 v121, v148, v120
	v_lshlrev_b64 v[142:143], 11, v[144:145]
	s_lshl_b32 s6, s14, 8
	v_lshl_add_u64 v[142:143], s[20:21], 0, v[142:143]
	s_ashr_i32 s7, s6, 31
	v_lshl_add_u64 v[142:143], s[6:7], 1, v[142:143]
	s_mov_b32 s69, s45
	v_lshl_add_u64 v[142:143], v[142:143], 0, s[68:69]
	v_lshl_add_u64 v[142:143], v[142:143], 0, v[136:137]
	v_cvt_pk_bf16_f32 v127, v122, v123
	s_mov_b64 s[6:7], 0x100
	global_store_dwordx4 v[142:143], v[124:127], off sc0 sc1
	s_nop 1
	v_cvt_pk_bf16_f32 v116, v116, v117
	v_cvt_pk_bf16_f32 v117, v118, v119
	v_cvt_pk_bf16_f32 v118, v112, v113
	v_cvt_pk_bf16_f32 v119, v114, v115
	s_waitcnt lgkmcnt(0)
	v_add_f32_e32 v114, v120, v121
	ds_bpermute_b32 v115, v149, v114
	v_lshl_add_u64 v[112:113], v[142:143], 0, s[6:7]
	global_store_dwordx4 v[112:113], v[116:119], off sc0 sc1
	s_nop 1
	v_readlane_b32 s6, v254, 60
	v_lshlrev_b64 v[112:113], 2, v[144:145]
	v_readlane_b32 s7, v254, 61
	s_nop 1
	v_lshl_add_u64 v[112:113], s[6:7], 0, v[112:113]
	s_and_saveexec_b64 s[6:7], s[0:1]
	s_cbranch_execz .LBB0_634
	s_mul_i32 s18, s14, 0x43000
	s_ashr_i32 s19, s18, 31
	s_waitcnt lgkmcnt(0)
	v_add_f32_e32 v116, v114, v115
	v_lshl_add_u64 v[114:115], s[18:19], 0, v[112:113]
	s_mul_i32 s44, s33, 0x10c00
	v_lshl_add_u64 v[114:115], v[114:115], 0, s[44:45]
	global_store_dword v[114:115], v116, off sc0 sc1
	s_nop 1
.LBB0_634:
	s_or_b64 exec, exec, s[6:7]
	v_mul_f32_e32 v116, v109, v109
	v_mul_f32_e32 v117, v111, v111
	v_fmac_f32_e32 v116, v108, v108
	v_fmac_f32_e32 v117, v110, v110
	v_add_f32_e32 v116, v116, v117
	v_mul_f32_e32 v117, v105, v105
	v_fmac_f32_e32 v117, v104, v104
	v_cvt_pk_bf16_f32 v108, v108, v109
	v_cvt_pk_bf16_f32 v109, v110, v111
	v_cvt_pk_bf16_f32 v110, v104, v105
	v_mul_f32_e32 v104, v101, v101
	v_mul_f32_e32 v105, v103, v103
	v_fmac_f32_e32 v104, v100, v100
	v_fmac_f32_e32 v105, v102, v102
	v_add_f32_e32 v104, v104, v105
	v_mul_f32_e32 v105, v97, v97
	v_fmac_f32_e32 v105, v96, v96
	v_add_f32_e32 v116, v116, v117
	v_mul_f32_e32 v117, v107, v107
	v_add_f32_e32 v104, v104, v105
	v_mul_f32_e32 v105, v99, v99
	v_fmac_f32_e32 v117, v106, v106
	v_fmac_f32_e32 v105, v98, v98
	v_add_f32_e32 v116, v117, v116
	v_add_f32_e32 v104, v105, v104
	v_add_f32_e32 v104, v116, v104
	ds_bpermute_b32 v105, v148, v104
	s_mov_b64 s[6:7], 0x8000
	s_waitcnt lgkmcnt(0)
	v_lshl_add_u64 v[114:115], v[142:143], 0, s[6:7]
	v_cvt_pk_bf16_f32 v111, v106, v107
	s_mov_b64 s[6:7], 0x8100
	global_store_dwordx4 v[114:115], v[108:111], off sc0 sc1
	s_nop 1
	v_cvt_pk_bf16_f32 v100, v100, v101
	v_cvt_pk_bf16_f32 v101, v102, v103
	v_cvt_pk_bf16_f32 v102, v96, v97
	v_add_f32_e32 v96, v104, v105
	ds_bpermute_b32 v97, v149, v96
	v_cvt_pk_bf16_f32 v103, v98, v99
	v_lshl_add_u64 v[98:99], v[142:143], 0, s[6:7]
	global_store_dwordx4 v[98:99], v[100:103], off sc0 sc1
	s_nop 1
	s_and_saveexec_b64 s[6:7], s[0:1]
	s_cbranch_execz .LBB0_636
	s_waitcnt lgkmcnt(0)
	v_add_f32_e32 v98, v96, v97
	v_or_b32_e32 v96, 16, v144
	v_ashrrev_i32_e32 v97, 31, v96
	v_readlane_b32 s12, v254, 60
	v_lshlrev_b64 v[96:97], 2, v[96:97]
	v_readlane_b32 s13, v254, 61
	s_mul_i32 s18, s14, 0x43000
	s_ashr_i32 s19, s18, 31
	v_lshl_add_u64 v[96:97], s[12:13], 0, v[96:97]
	v_lshl_add_u64 v[96:97], s[18:19], 0, v[96:97]
	s_mul_i32 s44, s33, 0x10c00
	v_lshl_add_u64 v[96:97], v[96:97], 0, s[44:45]
	global_store_dword v[96:97], v98, off sc0 sc1
	s_nop 1
.LBB0_636:
	s_or_b64 exec, exec, s[6:7]
	v_mul_f32_e32 v98, v93, v93
	v_mul_f32_e32 v99, v95, v95
	v_fmac_f32_e32 v98, v92, v92
	v_fmac_f32_e32 v99, v94, v94
	v_add_f32_e32 v98, v98, v99
	v_mul_f32_e32 v99, v89, v89
	v_fmac_f32_e32 v99, v88, v88
	v_cvt_pk_bf16_f32 v92, v92, v93
	v_cvt_pk_bf16_f32 v93, v94, v95
	v_cvt_pk_bf16_f32 v94, v88, v89
	v_mul_f32_e32 v88, v85, v85
	v_mul_f32_e32 v89, v87, v87
	v_fmac_f32_e32 v88, v84, v84
	v_fmac_f32_e32 v89, v86, v86
	v_add_f32_e32 v88, v88, v89
	v_mul_f32_e32 v89, v81, v81
	v_fmac_f32_e32 v89, v80, v80
	v_add_f32_e32 v98, v98, v99
	v_mul_f32_e32 v99, v91, v91
	v_add_f32_e32 v88, v88, v89
	v_mul_f32_e32 v89, v83, v83
	v_fmac_f32_e32 v99, v90, v90
	v_fmac_f32_e32 v89, v82, v82
	v_add_f32_e32 v98, v99, v98
	v_add_f32_e32 v88, v89, v88
	v_add_f32_e32 v88, v98, v88
	ds_bpermute_b32 v89, v148, v88
	s_mov_b64 s[6:7], 0x10000
	s_waitcnt lgkmcnt(0)
	v_lshl_add_u64 v[96:97], v[142:143], 0, s[6:7]
	v_cvt_pk_bf16_f32 v95, v90, v91
	s_mov_b64 s[6:7], 0x10100
	global_store_dwordx4 v[96:97], v[92:95], off sc0 sc1
	s_nop 1
	v_cvt_pk_bf16_f32 v84, v84, v85
	v_cvt_pk_bf16_f32 v85, v86, v87
	v_cvt_pk_bf16_f32 v86, v80, v81
	v_add_f32_e32 v80, v88, v89
	ds_bpermute_b32 v81, v149, v80
	v_cvt_pk_bf16_f32 v87, v82, v83
	v_lshl_add_u64 v[82:83], v[142:143], 0, s[6:7]
	global_store_dwordx4 v[82:83], v[84:87], off sc0 sc1
	s_nop 1
	s_and_saveexec_b64 s[6:7], s[0:1]
	s_cbranch_execz .LBB0_638
	s_waitcnt lgkmcnt(0)
	v_add_f32_e32 v82, v80, v81
	v_or_b32_e32 v80, 32, v144
	v_ashrrev_i32_e32 v81, 31, v80
	v_readlane_b32 s12, v254, 60
	v_lshlrev_b64 v[80:81], 2, v[80:81]
	v_readlane_b32 s13, v254, 61
	s_mul_i32 s18, s14, 0x43000
	s_ashr_i32 s19, s18, 31
	v_lshl_add_u64 v[80:81], s[12:13], 0, v[80:81]
	v_lshl_add_u64 v[80:81], s[18:19], 0, v[80:81]
	s_mul_i32 s44, s33, 0x10c00
	v_lshl_add_u64 v[80:81], v[80:81], 0, s[44:45]
	global_store_dword v[80:81], v82, off sc0 sc1
	s_nop 1
.LBB0_638:
	s_or_b64 exec, exec, s[6:7]
	v_mul_f32_e32 v82, v77, v77
	v_mul_f32_e32 v83, v79, v79
	v_fmac_f32_e32 v82, v76, v76
	v_fmac_f32_e32 v83, v78, v78
	v_add_f32_e32 v82, v82, v83
	v_mul_f32_e32 v83, v73, v73
	v_fmac_f32_e32 v83, v72, v72
	v_cvt_pk_bf16_f32 v76, v76, v77
	v_cvt_pk_bf16_f32 v77, v78, v79
	v_cvt_pk_bf16_f32 v78, v72, v73
	v_mul_f32_e32 v72, v69, v69
	v_mul_f32_e32 v73, v71, v71
	v_fmac_f32_e32 v72, v68, v68
	v_fmac_f32_e32 v73, v70, v70
	v_add_f32_e32 v72, v72, v73
	v_mul_f32_e32 v73, v65, v65
	v_fmac_f32_e32 v73, v64, v64
	v_add_f32_e32 v82, v82, v83
	v_mul_f32_e32 v83, v75, v75
	v_add_f32_e32 v72, v72, v73
	v_mul_f32_e32 v73, v67, v67
	v_fmac_f32_e32 v83, v74, v74
	v_fmac_f32_e32 v73, v66, v66
	v_add_f32_e32 v82, v83, v82
	v_add_f32_e32 v72, v73, v72
	v_add_f32_e32 v72, v82, v72
	ds_bpermute_b32 v73, v148, v72
	s_mov_b64 s[6:7], 0x18000
	s_waitcnt lgkmcnt(0)
	v_lshl_add_u64 v[80:81], v[142:143], 0, s[6:7]
	v_cvt_pk_bf16_f32 v79, v74, v75
	s_mov_b64 s[6:7], 0x18100
	global_store_dwordx4 v[80:81], v[76:79], off sc0 sc1
	s_nop 1
	v_cvt_pk_bf16_f32 v68, v68, v69
	v_cvt_pk_bf16_f32 v69, v70, v71
	v_cvt_pk_bf16_f32 v70, v64, v65
	v_add_f32_e32 v64, v72, v73
	ds_bpermute_b32 v65, v149, v64
	v_cvt_pk_bf16_f32 v71, v66, v67
	v_lshl_add_u64 v[66:67], v[142:143], 0, s[6:7]
	global_store_dwordx4 v[66:67], v[68:71], off sc0 sc1
	s_nop 1
	s_and_saveexec_b64 s[6:7], s[0:1]
	s_cbranch_execz .LBB0_640
	s_waitcnt lgkmcnt(0)
	v_add_f32_e32 v66, v64, v65
	v_or_b32_e32 v64, 48, v144
	v_ashrrev_i32_e32 v65, 31, v64
	v_readlane_b32 s12, v254, 60
	v_lshlrev_b64 v[64:65], 2, v[64:65]
	v_readlane_b32 s13, v254, 61
	s_mul_i32 s18, s14, 0x43000
	s_ashr_i32 s19, s18, 31
	v_lshl_add_u64 v[64:65], s[12:13], 0, v[64:65]
	v_lshl_add_u64 v[64:65], s[18:19], 0, v[64:65]
	s_mul_i32 s44, s33, 0x10c00
	v_lshl_add_u64 v[64:65], v[64:65], 0, s[44:45]
	global_store_dword v[64:65], v66, off sc0 sc1
	s_nop 1
.LBB0_640:
	s_or_b64 exec, exec, s[6:7]
	v_mul_f32_e32 v66, v61, v61
	v_mul_f32_e32 v67, v63, v63
	v_fmac_f32_e32 v66, v60, v60
	v_fmac_f32_e32 v67, v62, v62
	v_add_f32_e32 v66, v66, v67
	v_mul_f32_e32 v67, v57, v57
	v_fmac_f32_e32 v67, v56, v56
	v_cvt_pk_bf16_f32 v60, v60, v61
	v_cvt_pk_bf16_f32 v61, v62, v63
	v_cvt_pk_bf16_f32 v62, v56, v57
	v_mul_f32_e32 v56, v53, v53
	v_mul_f32_e32 v57, v55, v55
	v_fmac_f32_e32 v56, v52, v52
	v_fmac_f32_e32 v57, v54, v54
	v_add_f32_e32 v56, v56, v57
	v_mul_f32_e32 v57, v49, v49
	v_fmac_f32_e32 v57, v48, v48
	v_add_f32_e32 v66, v66, v67
	v_mul_f32_e32 v67, v59, v59
	v_add_f32_e32 v56, v56, v57
	v_mul_f32_e32 v57, v51, v51
	v_fmac_f32_e32 v67, v58, v58
	v_fmac_f32_e32 v57, v50, v50
	v_add_f32_e32 v66, v67, v66
	v_add_f32_e32 v56, v57, v56
	v_add_f32_e32 v56, v66, v56
	ds_bpermute_b32 v57, v148, v56
	s_mov_b64 s[6:7], 0x40000
	s_waitcnt lgkmcnt(0)
	v_lshl_add_u64 v[64:65], v[142:143], 0, s[6:7]
	v_cvt_pk_bf16_f32 v63, v58, v59
	s_mov_b64 s[6:7], 0x40100
	global_store_dwordx4 v[64:65], v[60:63], off sc0 sc1
	s_nop 1
	v_cvt_pk_bf16_f32 v52, v52, v53
	v_cvt_pk_bf16_f32 v53, v54, v55
	v_cvt_pk_bf16_f32 v54, v48, v49
	v_add_f32_e32 v48, v56, v57
	ds_bpermute_b32 v49, v149, v48
	v_cvt_pk_bf16_f32 v55, v50, v51
	v_lshl_add_u64 v[50:51], v[142:143], 0, s[6:7]
	global_store_dwordx4 v[50:51], v[52:55], off sc0 sc1
	s_nop 1
	s_and_saveexec_b64 s[6:7], s[0:1]
	s_cbranch_execz .LBB0_642
	s_mul_i32 s18, s14, 0x43000
	s_ashr_i32 s19, s18, 31
	s_waitcnt lgkmcnt(0)
	v_add_f32_e32 v50, v48, v49
	v_lshl_add_u64 v[48:49], s[18:19], 0, v[112:113]
	s_mul_i32 s44, s33, 0x10c00
	v_lshl_add_u64 v[48:49], v[48:49], 0, s[44:45]
	s_mov_b64 s[18:19], 0x200
	v_lshl_add_u64 v[48:49], v[48:49], 0, s[18:19]
	global_store_dword v[48:49], v50, off sc0 sc1
	s_nop 1
.LBB0_642:
	s_or_b64 exec, exec, s[6:7]
	v_mul_f32_e32 v50, v45, v45
	v_mul_f32_e32 v51, v47, v47
	v_fmac_f32_e32 v50, v44, v44
	v_fmac_f32_e32 v51, v46, v46
	v_add_f32_e32 v50, v50, v51
	v_mul_f32_e32 v51, v41, v41
	v_fmac_f32_e32 v51, v40, v40
	v_cvt_pk_bf16_f32 v44, v44, v45
	v_cvt_pk_bf16_f32 v45, v46, v47
	v_cvt_pk_bf16_f32 v46, v40, v41
	v_mul_f32_e32 v40, v37, v37
	v_mul_f32_e32 v41, v39, v39
	v_fmac_f32_e32 v40, v36, v36
	v_fmac_f32_e32 v41, v38, v38
	v_add_f32_e32 v40, v40, v41
	v_mul_f32_e32 v41, v33, v33
	v_fmac_f32_e32 v41, v32, v32
	v_add_f32_e32 v50, v50, v51
	v_mul_f32_e32 v51, v43, v43
	v_add_f32_e32 v40, v40, v41
	v_mul_f32_e32 v41, v35, v35
	v_fmac_f32_e32 v51, v42, v42
	v_fmac_f32_e32 v41, v34, v34
	v_add_f32_e32 v50, v51, v50
	v_add_f32_e32 v40, v41, v40
	v_add_f32_e32 v40, v50, v40
	ds_bpermute_b32 v41, v148, v40
	s_mov_b64 s[6:7], 0x48000
	s_waitcnt lgkmcnt(0)
	v_lshl_add_u64 v[48:49], v[142:143], 0, s[6:7]
	v_cvt_pk_bf16_f32 v47, v42, v43
	s_mov_b64 s[6:7], 0x48100
	global_store_dwordx4 v[48:49], v[44:47], off sc0 sc1
	s_nop 1
	v_cvt_pk_bf16_f32 v36, v36, v37
	v_cvt_pk_bf16_f32 v37, v38, v39
	v_cvt_pk_bf16_f32 v38, v32, v33
	v_add_f32_e32 v32, v40, v41
	ds_bpermute_b32 v33, v149, v32
	v_cvt_pk_bf16_f32 v39, v34, v35
	v_lshl_add_u64 v[34:35], v[142:143], 0, s[6:7]
	global_store_dwordx4 v[34:35], v[36:39], off sc0 sc1
	s_nop 1
	s_and_saveexec_b64 s[6:7], s[0:1]
	s_cbranch_execz .LBB0_644
	s_mul_i32 s18, s14, 0x43000
	s_ashr_i32 s19, s18, 31
	s_waitcnt lgkmcnt(0)
	v_add_f32_e32 v34, v32, v33
	v_lshl_add_u64 v[32:33], s[18:19], 0, v[112:113]
	s_mul_i32 s44, s33, 0x10c00
	v_lshl_add_u64 v[32:33], v[32:33], 0, s[44:45]
	s_mov_b64 s[18:19], 0x240
	v_lshl_add_u64 v[32:33], v[32:33], 0, s[18:19]
	global_store_dword v[32:33], v34, off sc0 sc1
	s_nop 1
.LBB0_644:
	s_or_b64 exec, exec, s[6:7]
	v_mul_f32_e32 v34, v29, v29
	v_mul_f32_e32 v35, v31, v31
	v_fmac_f32_e32 v34, v28, v28
	v_fmac_f32_e32 v35, v30, v30
	v_add_f32_e32 v34, v34, v35
	v_mul_f32_e32 v35, v25, v25
	v_fmac_f32_e32 v35, v24, v24
	v_cvt_pk_bf16_f32 v28, v28, v29
	v_cvt_pk_bf16_f32 v29, v30, v31
	v_cvt_pk_bf16_f32 v30, v24, v25
	v_mul_f32_e32 v24, v21, v21
	v_mul_f32_e32 v25, v23, v23
	v_fmac_f32_e32 v24, v20, v20
	v_fmac_f32_e32 v25, v22, v22
	v_add_f32_e32 v24, v24, v25
	v_mul_f32_e32 v25, v17, v17
	v_fmac_f32_e32 v25, v16, v16
	v_add_f32_e32 v34, v34, v35
	v_mul_f32_e32 v35, v27, v27
	v_add_f32_e32 v24, v24, v25
	v_mul_f32_e32 v25, v19, v19
	v_fmac_f32_e32 v35, v26, v26
	v_fmac_f32_e32 v25, v18, v18
	v_add_f32_e32 v34, v35, v34
	v_add_f32_e32 v24, v25, v24
	v_add_f32_e32 v24, v34, v24
	ds_bpermute_b32 v25, v148, v24
	s_mov_b64 s[6:7], 0x50000
	s_waitcnt lgkmcnt(0)
	v_lshl_add_u64 v[32:33], v[142:143], 0, s[6:7]
	v_cvt_pk_bf16_f32 v31, v26, v27
	s_mov_b64 s[6:7], 0x50100
	global_store_dwordx4 v[32:33], v[28:31], off sc0 sc1
	s_nop 1
	v_cvt_pk_bf16_f32 v20, v20, v21
	v_cvt_pk_bf16_f32 v21, v22, v23
	v_cvt_pk_bf16_f32 v22, v16, v17
	v_add_f32_e32 v16, v24, v25
	ds_bpermute_b32 v17, v149, v16
	v_cvt_pk_bf16_f32 v23, v18, v19
	v_lshl_add_u64 v[18:19], v[142:143], 0, s[6:7]
	global_store_dwordx4 v[18:19], v[20:23], off sc0 sc1
	s_nop 1
	s_and_saveexec_b64 s[6:7], s[0:1]
	s_cbranch_execz .LBB0_646
	s_mul_i32 s18, s14, 0x43000
	s_ashr_i32 s19, s18, 31
	s_waitcnt lgkmcnt(0)
	v_add_f32_e32 v18, v16, v17
	v_lshl_add_u64 v[16:17], s[18:19], 0, v[112:113]
	s_mul_i32 s44, s33, 0x10c00
	v_lshl_add_u64 v[16:17], v[16:17], 0, s[44:45]
	s_mov_b64 s[18:19], 0x280
	v_lshl_add_u64 v[16:17], v[16:17], 0, s[18:19]
	global_store_dword v[16:17], v18, off sc0 sc1
	s_nop 1
.LBB0_646:
	s_or_b64 exec, exec, s[6:7]
	v_mul_f32_e32 v18, v13, v13
	v_mul_f32_e32 v19, v15, v15
	v_fmac_f32_e32 v18, v12, v12
	v_fmac_f32_e32 v19, v14, v14
	v_add_f32_e32 v18, v18, v19
	v_mul_f32_e32 v19, v9, v9
	v_fmac_f32_e32 v19, v8, v8
	v_cvt_pk_bf16_f32 v12, v12, v13
	v_cvt_pk_bf16_f32 v13, v14, v15
	v_cvt_pk_bf16_f32 v14, v8, v9
	v_mul_f32_e32 v8, v5, v5
	v_mul_f32_e32 v9, v7, v7
	v_fmac_f32_e32 v8, v4, v4
	v_fmac_f32_e32 v9, v6, v6
	v_add_f32_e32 v8, v8, v9
	v_mul_f32_e32 v9, v1, v1
	v_fmac_f32_e32 v9, v0, v0
	v_add_f32_e32 v18, v18, v19
	v_mul_f32_e32 v19, v11, v11
	v_add_f32_e32 v8, v8, v9
	v_mul_f32_e32 v9, v3, v3
	v_fmac_f32_e32 v19, v10, v10
	v_fmac_f32_e32 v9, v2, v2
	v_add_f32_e32 v18, v19, v18
	v_add_f32_e32 v8, v9, v8
	v_add_f32_e32 v8, v18, v8
	ds_bpermute_b32 v9, v148, v8
	s_mov_b64 s[6:7], 0x58000
	s_waitcnt lgkmcnt(0)
	v_lshl_add_u64 v[16:17], v[142:143], 0, s[6:7]
	v_cvt_pk_bf16_f32 v15, v10, v11
	s_mov_b64 s[6:7], 0x58100
	global_store_dwordx4 v[16:17], v[12:15], off sc0 sc1
	s_nop 1
	v_cvt_pk_bf16_f32 v4, v4, v5
	v_cvt_pk_bf16_f32 v5, v6, v7
	v_cvt_pk_bf16_f32 v6, v0, v1
	v_add_f32_e32 v0, v8, v9
	ds_bpermute_b32 v1, v149, v0
	v_cvt_pk_bf16_f32 v7, v2, v3
	v_lshl_add_u64 v[2:3], v[142:143], 0, s[6:7]
	global_store_dwordx4 v[2:3], v[4:7], off sc0 sc1
	s_nop 1
	s_and_saveexec_b64 s[6:7], s[0:1]
	s_cbranch_execz .LBB0_648
	s_mul_i32 s14, s14, 0x43000
	s_ashr_i32 s15, s14, 31
	s_waitcnt lgkmcnt(0)
	v_add_f32_e32 v2, v0, v1
	v_lshl_add_u64 v[0:1], s[14:15], 0, v[112:113]
	s_mul_i32 s44, s33, 0x10c00
	v_lshl_add_u64 v[0:1], v[0:1], 0, s[44:45]
	s_mov_b64 s[14:15], 0x2c0
	v_lshl_add_u64 v[0:1], v[0:1], 0, s[14:15]
	global_store_dword v[0:1], v2, off sc0 sc1
	s_nop 1

.LBB0_727:
	s_add_u32 s0, s24, 0x44000
	v_writelane_b32 v255, s0, 2
	s_addc_u32 s0, s25, 0
	s_add_u32 s58, s24, 0x74200
	s_addc_u32 s59, s25, 0
	s_lshl_b32 s3, s91, 2
	v_add_u32_e32 v32, 64, v182
	v_cmp_lt_i32_e32 vcc, v181, v32
	s_add_u32 s44, s22, 0x4000000
	v_writelane_b32 v255, s0, 3
	v_cndmask_b32_e32 v33, v152, v181, vcc
	v_cmp_lt_i32_e32 vcc, v180, v32
	v_readlane_b32 s0, v254, 60
	s_addc_u32 s45, s23, 0
	v_lshlrev_b32_e32 v148, 2, v33
	v_cndmask_b32_e32 v33, v152, v180, vcc
	v_cmp_lt_i32_e32 vcc, v179, v32
	v_readlane_b32 s1, v254, 61
	s_add_u32 s46, s24, 0x3100000
	v_lshlrev_b32_e32 v149, 2, v33
	v_cndmask_b32_e32 v33, v152, v179, vcc
	v_cmp_lt_i32_e32 vcc, v178, v32
	v_mul_u32_u24_e32 v52, 0x10c00, v48
	v_mov_b32_e32 v53, 0
	v_lshl_add_u64 v[52:53], v[52:53], 0, s[0:1]
	s_addc_u32 s47, s25, 0
	s_add_i32 s0, s3, 0xffffc000
	v_lshlrev_b32_e32 v150, 2, v33
	v_cndmask_b32_e32 v33, v152, v178, vcc
	v_cmp_lt_i32_e32 vcc, v177, v32
	v_writelane_b32 v254, s0, 57
	s_lshr_b32 s0, s6, 4
	v_lshlrev_b32_e32 v151, 2, v33
	v_cndmask_b32_e32 v33, v152, v177, vcc
	v_cmp_lt_i32_e32 vcc, v176, v32
	s_and_b32 s0, s0, 0xfffc
	v_writelane_b32 v254, s0, 55
	v_cndmask_b32_e32 v32, v152, v176, vcc
	s_add_i32 s0, s3, -16
	v_lshlrev_b32_e32 v154, 2, v33
	v_lshlrev_b32_e32 v155, 2, v32
	v_lshlrev_b64 v[32:33], 3, v[48:49]
	v_writelane_b32 v254, s0, 53
	s_add_i32 s0, s3, 0xffffbf80
	s_add_i32 s27, 0, 0x20080
	v_cmp_gt_i32_e64 s[12:13], 16, v48
	v_lshl_add_u64 v[54:55], s[30:31], 0, v[32:33]
	v_lshl_add_u64 v[56:57], s[20:21], 0, v[32:33]
	v_lshl_add_u64 v[58:59], s[24:25], 0, v[32:33]
	v_writelane_b32 v254, s3, 58
	v_writelane_b32 v255, s0, 4
	s_mov_b32 s3, -1
	s_mov_b32 s69, 0
	v_mov_b32_e32 v61, 0
	v_mov_b32_e32 v102, 0x358637bd
	s_mov_b32 s84, 0x800000
	s_mov_b64 s[70:71], 0x800
	s_mov_b64 s[72:73], 0xa00
	s_mov_b64 s[74:75], 0xc00
	s_mov_b64 s[78:79], 0xe00
	s_mov_b64 s[42:43], 0x200
	s_mov_b64 s[28:29], 0x400
	v_mov_b32_e32 v103, 0x80
	v_mov_b32_e32 v104, s27
	s_branch .LBB0_730

.LBB0_873:
	s_mov_b32 s87, s69
	v_mov_b32_e32 v32, 0
	s_and_saveexec_b64 s[48:49], s[12:13]
	s_cbranch_execz .LBB0_875
	s_lshl_b64 s[16:17], s[86:87], 2
	v_lshl_add_u64 v[32:33], v[52:53], 0, s[16:17]
	global_load_dword v32, v[32:33], off

.LBB0_914:
	v_mov_b32_e32 v32, 0
	s_and_saveexec_b64 s[48:49], s[12:13]
	s_cbranch_execz .LBB0_916
	s_lshl_b64 s[16:17], s[68:69], 2
	v_lshl_add_u64 v[32:33], v[52:53], 0, s[16:17]
	global_load_dword v32, v[32:33], off

.LBB0_996:
	v_mov_b32_e32 v32, 0
	s_and_saveexec_b64 s[40:41], s[12:13]
	s_cbranch_execz .LBB0_998
	s_lshl_b64 s[16:17], s[68:69], 2
	v_lshl_add_u64 v[32:33], v[52:53], 0, s[16:17]
	global_load_dword v32, v[32:33], off

.LBB0_1259:
	v_mul_f32_e32 v157, v125, v125
	v_mul_f32_e32 v158, v127, v127
	v_fmac_f32_e32 v157, v124, v124
	v_fmac_f32_e32 v158, v126, v126
	v_add_f32_e32 v157, v157, v158
	v_mul_f32_e32 v158, v121, v121
	v_fmac_f32_e32 v158, v120, v120
	v_cvt_pk_bf16_f32 v124, v124, v125
	v_cvt_pk_bf16_f32 v125, v126, v127
	v_cvt_pk_bf16_f32 v126, v120, v121
	v_mul_f32_e32 v120, v117, v117
	v_mul_f32_e32 v121, v119, v119
	v_fmac_f32_e32 v120, v116, v116
	v_fmac_f32_e32 v121, v118, v118
	v_add_f32_e32 v120, v120, v121
	v_mul_f32_e32 v121, v113, v113
	v_fmac_f32_e32 v121, v112, v112
	v_add_f32_e32 v157, v157, v158
	v_mul_f32_e32 v158, v123, v123
	v_add_f32_e32 v120, v120, v121
	v_mul_f32_e32 v121, v115, v115
	v_fmac_f32_e32 v158, v122, v122
	v_fmac_f32_e32 v121, v114, v114
	v_add_f32_e32 v157, v158, v157
	v_add_f32_e32 v120, v121, v120
	v_lshl_add_u32 v144, s3, 8, v146
	v_add_f32_e32 v120, v157, v120
	v_ashrrev_i32_e32 v145, 31, v144
	ds_bpermute_b32 v121, v154, v120
	v_lshlrev_b64 v[142:143], 11, v[144:145]
	s_lshl_b32 s6, s10, 8
	v_lshl_add_u64 v[142:143], s[20:21], 0, v[142:143]
	s_ashr_i32 s7, s6, 31
	v_lshl_add_u64 v[142:143], s[6:7], 1, v[142:143]
	s_mov_b32 s71, s57
	v_lshl_add_u64 v[142:143], v[142:143], 0, s[70:71]
	v_lshl_add_u64 v[142:143], v[142:143], 0, v[136:137]
	v_cvt_pk_bf16_f32 v127, v122, v123
	s_mov_b64 s[6:7], 0x100
	global_store_dwordx4 v[142:143], v[124:127], off sc0 sc1
	s_nop 1
	v_cvt_pk_bf16_f32 v116, v116, v117
	v_cvt_pk_bf16_f32 v117, v118, v119
	v_cvt_pk_bf16_f32 v118, v112, v113
	v_cvt_pk_bf16_f32 v119, v114, v115
	s_waitcnt lgkmcnt(0)
	v_add_f32_e32 v114, v120, v121
	ds_bpermute_b32 v115, v155, v114
	v_lshl_add_u64 v[112:113], v[142:143], 0, s[6:7]
	global_store_dwordx4 v[112:113], v[116:119], off sc0 sc1
	s_nop 1
	v_readlane_b32 s6, v254, 60
	v_lshlrev_b64 v[112:113], 2, v[144:145]
	v_readlane_b32 s7, v254, 61
	s_nop 1
	v_lshl_add_u64 v[112:113], s[6:7], 0, v[112:113]
	s_and_saveexec_b64 s[6:7], s[0:1]
	s_cbranch_execz .LBB0_1261
	s_mul_i32 s8, s10, 0x43000
	s_ashr_i32 s9, s8, 31
	s_waitcnt lgkmcnt(0)
	v_add_f32_e32 v116, v114, v115
	v_lshl_add_u64 v[114:115], s[8:9], 0, v[112:113]
	s_mul_i32 s56, s33, 0x10c00
	v_lshl_add_u64 v[114:115], v[114:115], 0, s[56:57]
	global_store_dword v[114:115], v116, off sc0 sc1
	s_nop 1
.LBB0_1261:
	s_or_b64 exec, exec, s[6:7]
	v_mul_f32_e32 v116, v109, v109
	v_mul_f32_e32 v117, v111, v111
	v_fmac_f32_e32 v116, v108, v108
	v_fmac_f32_e32 v117, v110, v110
	v_add_f32_e32 v116, v116, v117
	v_mul_f32_e32 v117, v105, v105
	v_fmac_f32_e32 v117, v104, v104
	v_cvt_pk_bf16_f32 v108, v108, v109
	v_cvt_pk_bf16_f32 v109, v110, v111
	v_cvt_pk_bf16_f32 v110, v104, v105
	v_mul_f32_e32 v104, v101, v101
	v_mul_f32_e32 v105, v103, v103
	v_fmac_f32_e32 v104, v100, v100
	v_fmac_f32_e32 v105, v102, v102
	v_add_f32_e32 v104, v104, v105
	v_mul_f32_e32 v105, v97, v97
	v_fmac_f32_e32 v105, v96, v96
	v_add_f32_e32 v116, v116, v117
	v_mul_f32_e32 v117, v107, v107
	v_add_f32_e32 v104, v104, v105
	v_mul_f32_e32 v105, v99, v99
	v_fmac_f32_e32 v117, v106, v106
	v_fmac_f32_e32 v105, v98, v98
	v_add_f32_e32 v116, v117, v116
	v_add_f32_e32 v104, v105, v104
	v_add_f32_e32 v104, v116, v104
	ds_bpermute_b32 v105, v154, v104
	s_mov_b64 s[6:7], 0x8000
	s_waitcnt lgkmcnt(0)
	v_lshl_add_u64 v[114:115], v[142:143], 0, s[6:7]
	v_cvt_pk_bf16_f32 v111, v106, v107
	s_mov_b64 s[6:7], 0x8100
	global_store_dwordx4 v[114:115], v[108:111], off sc0 sc1
	s_nop 1
	v_cvt_pk_bf16_f32 v100, v100, v101
	v_cvt_pk_bf16_f32 v101, v102, v103
	v_cvt_pk_bf16_f32 v102, v96, v97
	v_add_f32_e32 v96, v104, v105
	ds_bpermute_b32 v97, v155, v96
	v_cvt_pk_bf16_f32 v103, v98, v99
	v_lshl_add_u64 v[98:99], v[142:143], 0, s[6:7]
	global_store_dwordx4 v[98:99], v[100:103], off sc0 sc1
	s_nop 1
	s_and_saveexec_b64 s[6:7], s[0:1]
	s_cbranch_execz .LBB0_1263
	s_waitcnt lgkmcnt(0)
	v_add_f32_e32 v98, v96, v97
	v_or_b32_e32 v96, 16, v144
	v_ashrrev_i32_e32 v97, 31, v96
	v_readlane_b32 s8, v254, 60
	v_lshlrev_b64 v[96:97], 2, v[96:97]
	v_readlane_b32 s9, v254, 61
	s_mul_i32 s56, s33, 0x10c00
	s_nop 0
	v_lshl_add_u64 v[96:97], s[8:9], 0, v[96:97]
	s_mul_i32 s8, s10, 0x43000
	s_ashr_i32 s9, s8, 31
	v_lshl_add_u64 v[96:97], s[8:9], 0, v[96:97]
	v_lshl_add_u64 v[96:97], v[96:97], 0, s[56:57]
	global_store_dword v[96:97], v98, off sc0 sc1
	s_nop 1
.LBB0_1263:
	s_or_b64 exec, exec, s[6:7]
	v_mul_f32_e32 v98, v93, v93
	v_mul_f32_e32 v99, v95, v95
	v_fmac_f32_e32 v98, v92, v92
	v_fmac_f32_e32 v99, v94, v94
	v_add_f32_e32 v98, v98, v99
	v_mul_f32_e32 v99, v89, v89
	v_fmac_f32_e32 v99, v88, v88
	v_cvt_pk_bf16_f32 v92, v92, v93
	v_cvt_pk_bf16_f32 v93, v94, v95
	v_cvt_pk_bf16_f32 v94, v88, v89
	v_mul_f32_e32 v88, v85, v85
	v_mul_f32_e32 v89, v87, v87
	v_fmac_f32_e32 v88, v84, v84
	v_fmac_f32_e32 v89, v86, v86
	v_add_f32_e32 v88, v88, v89
	v_mul_f32_e32 v89, v81, v81
	v_fmac_f32_e32 v89, v80, v80
	v_add_f32_e32 v98, v98, v99
	v_mul_f32_e32 v99, v91, v91
	v_add_f32_e32 v88, v88, v89
	v_mul_f32_e32 v89, v83, v83
	v_fmac_f32_e32 v99, v90, v90
	v_fmac_f32_e32 v89, v82, v82
	v_add_f32_e32 v98, v99, v98
	v_add_f32_e32 v88, v89, v88
	v_add_f32_e32 v88, v98, v88
	ds_bpermute_b32 v89, v154, v88
	s_mov_b64 s[6:7], 0x10000
	s_waitcnt lgkmcnt(0)
	v_lshl_add_u64 v[96:97], v[142:143], 0, s[6:7]
	v_cvt_pk_bf16_f32 v95, v90, v91
	s_mov_b64 s[6:7], 0x10100
	global_store_dwordx4 v[96:97], v[92:95], off sc0 sc1
	s_nop 1
	v_cvt_pk_bf16_f32 v84, v84, v85
	v_cvt_pk_bf16_f32 v85, v86, v87
	v_cvt_pk_bf16_f32 v86, v80, v81
	v_add_f32_e32 v80, v88, v89
	ds_bpermute_b32 v81, v155, v80
	v_cvt_pk_bf16_f32 v87, v82, v83
	v_lshl_add_u64 v[82:83], v[142:143], 0, s[6:7]
	global_store_dwordx4 v[82:83], v[84:87], off sc0 sc1
	s_nop 1
	s_and_saveexec_b64 s[6:7], s[0:1]
	s_cbranch_execz .LBB0_1265
	s_waitcnt lgkmcnt(0)
	v_add_f32_e32 v82, v80, v81
	v_or_b32_e32 v80, 32, v144
	v_ashrrev_i32_e32 v81, 31, v80
	v_readlane_b32 s8, v254, 60
	v_lshlrev_b64 v[80:81], 2, v[80:81]
	v_readlane_b32 s9, v254, 61
	s_mul_i32 s56, s33, 0x10c00
	s_nop 0
	v_lshl_add_u64 v[80:81], s[8:9], 0, v[80:81]
	s_mul_i32 s8, s10, 0x43000
	s_ashr_i32 s9, s8, 31
	v_lshl_add_u64 v[80:81], s[8:9], 0, v[80:81]
	v_lshl_add_u64 v[80:81], v[80:81], 0, s[56:57]
	global_store_dword v[80:81], v82, off sc0 sc1
	s_nop 1
.LBB0_1265:
	s_or_b64 exec, exec, s[6:7]
	v_mul_f32_e32 v82, v77, v77
	v_mul_f32_e32 v83, v79, v79
	v_fmac_f32_e32 v82, v76, v76
	v_fmac_f32_e32 v83, v78, v78
	v_add_f32_e32 v82, v82, v83
	v_mul_f32_e32 v83, v73, v73
	v_fmac_f32_e32 v83, v72, v72
	v_cvt_pk_bf16_f32 v76, v76, v77
	v_cvt_pk_bf16_f32 v77, v78, v79
	v_cvt_pk_bf16_f32 v78, v72, v73
	v_mul_f32_e32 v72, v69, v69
	v_mul_f32_e32 v73, v71, v71
	v_fmac_f32_e32 v72, v68, v68
	v_fmac_f32_e32 v73, v70, v70
	v_add_f32_e32 v72, v72, v73
	v_mul_f32_e32 v73, v65, v65
	v_fmac_f32_e32 v73, v64, v64
	v_add_f32_e32 v82, v82, v83
	v_mul_f32_e32 v83, v75, v75
	v_add_f32_e32 v72, v72, v73
	v_mul_f32_e32 v73, v67, v67
	v_fmac_f32_e32 v83, v74, v74
	v_fmac_f32_e32 v73, v66, v66
	v_add_f32_e32 v82, v83, v82
	v_add_f32_e32 v72, v73, v72
	v_add_f32_e32 v72, v82, v72
	ds_bpermute_b32 v73, v154, v72
	s_mov_b64 s[6:7], 0x18000
	s_waitcnt lgkmcnt(0)
	v_lshl_add_u64 v[80:81], v[142:143], 0, s[6:7]
	v_cvt_pk_bf16_f32 v79, v74, v75
	s_mov_b64 s[6:7], 0x18100
	global_store_dwordx4 v[80:81], v[76:79], off sc0 sc1
	s_nop 1
	v_cvt_pk_bf16_f32 v68, v68, v69
	v_cvt_pk_bf16_f32 v69, v70, v71
	v_cvt_pk_bf16_f32 v70, v64, v65
	v_add_f32_e32 v64, v72, v73
	ds_bpermute_b32 v65, v155, v64
	v_cvt_pk_bf16_f32 v71, v66, v67
	v_lshl_add_u64 v[66:67], v[142:143], 0, s[6:7]
	global_store_dwordx4 v[66:67], v[68:71], off sc0 sc1
	s_nop 1
	s_and_saveexec_b64 s[6:7], s[0:1]
	s_cbranch_execz .LBB0_1267
	s_waitcnt lgkmcnt(0)
	v_add_f32_e32 v66, v64, v65
	v_or_b32_e32 v64, 48, v144
	v_ashrrev_i32_e32 v65, 31, v64
	v_readlane_b32 s8, v254, 60
	v_lshlrev_b64 v[64:65], 2, v[64:65]
	v_readlane_b32 s9, v254, 61
	s_mul_i32 s56, s33, 0x10c00
	s_nop 0
	v_lshl_add_u64 v[64:65], s[8:9], 0, v[64:65]
	s_mul_i32 s8, s10, 0x43000
	s_ashr_i32 s9, s8, 31
	v_lshl_add_u64 v[64:65], s[8:9], 0, v[64:65]
	v_lshl_add_u64 v[64:65], v[64:65], 0, s[56:57]
	global_store_dword v[64:65], v66, off sc0 sc1
	s_nop 1
.LBB0_1267:
	s_or_b64 exec, exec, s[6:7]
	v_mul_f32_e32 v66, v61, v61
	v_mul_f32_e32 v67, v63, v63
	v_fmac_f32_e32 v66, v60, v60
	v_fmac_f32_e32 v67, v62, v62
	v_add_f32_e32 v66, v66, v67
	v_mul_f32_e32 v67, v57, v57
	v_fmac_f32_e32 v67, v56, v56
	v_cvt_pk_bf16_f32 v60, v60, v61
	v_cvt_pk_bf16_f32 v61, v62, v63
	v_cvt_pk_bf16_f32 v62, v56, v57
	v_mul_f32_e32 v56, v53, v53
	v_mul_f32_e32 v57, v55, v55
	v_fmac_f32_e32 v56, v52, v52
	v_fmac_f32_e32 v57, v54, v54
	v_add_f32_e32 v56, v56, v57
	v_mul_f32_e32 v57, v49, v49
	v_fmac_f32_e32 v57, v48, v48
	v_add_f32_e32 v66, v66, v67
	v_mul_f32_e32 v67, v59, v59
	v_add_f32_e32 v56, v56, v57
	v_mul_f32_e32 v57, v51, v51
	v_fmac_f32_e32 v67, v58, v58
	v_fmac_f32_e32 v57, v50, v50
	v_add_f32_e32 v66, v67, v66
	v_add_f32_e32 v56, v57, v56
	v_add_f32_e32 v56, v66, v56
	ds_bpermute_b32 v57, v154, v56
	s_mov_b64 s[6:7], 0x40000
	s_waitcnt lgkmcnt(0)
	v_lshl_add_u64 v[64:65], v[142:143], 0, s[6:7]
	v_cvt_pk_bf16_f32 v63, v58, v59
	s_mov_b64 s[6:7], 0x40100
	global_store_dwordx4 v[64:65], v[60:63], off sc0 sc1
	s_nop 1
	v_cvt_pk_bf16_f32 v52, v52, v53
	v_cvt_pk_bf16_f32 v53, v54, v55
	v_cvt_pk_bf16_f32 v54, v48, v49
	v_add_f32_e32 v48, v56, v57
	ds_bpermute_b32 v49, v155, v48
	v_cvt_pk_bf16_f32 v55, v50, v51
	v_lshl_add_u64 v[50:51], v[142:143], 0, s[6:7]
	global_store_dwordx4 v[50:51], v[52:55], off sc0 sc1
	s_nop 1
	s_and_saveexec_b64 s[6:7], s[0:1]
	s_cbranch_execz .LBB0_1269
	s_mul_i32 s8, s10, 0x43000
	s_ashr_i32 s9, s8, 31
	s_waitcnt lgkmcnt(0)
	v_add_f32_e32 v50, v48, v49
	v_lshl_add_u64 v[48:49], s[8:9], 0, v[112:113]
	s_mul_i32 s56, s33, 0x10c00
	v_lshl_add_u64 v[48:49], v[48:49], 0, s[56:57]
	s_mov_b64 s[8:9], 0x200
	v_lshl_add_u64 v[48:49], v[48:49], 0, s[8:9]
	global_store_dword v[48:49], v50, off sc0 sc1
	s_nop 1
.LBB0_1269:
	s_or_b64 exec, exec, s[6:7]
	v_mul_f32_e32 v50, v45, v45
	v_mul_f32_e32 v51, v47, v47
	v_fmac_f32_e32 v50, v44, v44
	v_fmac_f32_e32 v51, v46, v46
	v_add_f32_e32 v50, v50, v51
	v_mul_f32_e32 v51, v41, v41
	v_fmac_f32_e32 v51, v40, v40
	v_cvt_pk_bf16_f32 v44, v44, v45
	v_cvt_pk_bf16_f32 v45, v46, v47
	v_cvt_pk_bf16_f32 v46, v40, v41
	v_mul_f32_e32 v40, v37, v37
	v_mul_f32_e32 v41, v39, v39
	v_fmac_f32_e32 v40, v36, v36
	v_fmac_f32_e32 v41, v38, v38
	v_add_f32_e32 v40, v40, v41
	v_mul_f32_e32 v41, v33, v33
	v_fmac_f32_e32 v41, v32, v32
	v_add_f32_e32 v50, v50, v51
	v_mul_f32_e32 v51, v43, v43
	v_add_f32_e32 v40, v40, v41
	v_mul_f32_e32 v41, v35, v35
	v_fmac_f32_e32 v51, v42, v42
	v_fmac_f32_e32 v41, v34, v34
	v_add_f32_e32 v50, v51, v50
	v_add_f32_e32 v40, v41, v40
	v_add_f32_e32 v40, v50, v40
	ds_bpermute_b32 v41, v154, v40
	s_mov_b64 s[6:7], 0x48000
	s_waitcnt lgkmcnt(0)
	v_lshl_add_u64 v[48:49], v[142:143], 0, s[6:7]
	v_cvt_pk_bf16_f32 v47, v42, v43
	s_mov_b64 s[6:7], 0x48100
	global_store_dwordx4 v[48:49], v[44:47], off sc0 sc1
	s_nop 1
	v_cvt_pk_bf16_f32 v36, v36, v37
	v_cvt_pk_bf16_f32 v37, v38, v39
	v_cvt_pk_bf16_f32 v38, v32, v33
	v_add_f32_e32 v32, v40, v41
	ds_bpermute_b32 v33, v155, v32
	v_cvt_pk_bf16_f32 v39, v34, v35
	v_lshl_add_u64 v[34:35], v[142:143], 0, s[6:7]
	global_store_dwordx4 v[34:35], v[36:39], off sc0 sc1
	s_nop 1
	s_and_saveexec_b64 s[6:7], s[0:1]
	s_cbranch_execz .LBB0_1271
	s_mul_i32 s8, s10, 0x43000
	s_ashr_i32 s9, s8, 31
	s_waitcnt lgkmcnt(0)
	v_add_f32_e32 v34, v32, v33
	v_lshl_add_u64 v[32:33], s[8:9], 0, v[112:113]
	s_mul_i32 s56, s33, 0x10c00
	v_lshl_add_u64 v[32:33], v[32:33], 0, s[56:57]
	s_mov_b64 s[8:9], 0x240
	v_lshl_add_u64 v[32:33], v[32:33], 0, s[8:9]
	global_store_dword v[32:33], v34, off sc0 sc1
	s_nop 1
.LBB0_1271:
	s_or_b64 exec, exec, s[6:7]
	v_mul_f32_e32 v34, v29, v29
	v_mul_f32_e32 v35, v31, v31
	v_fmac_f32_e32 v34, v28, v28
	v_fmac_f32_e32 v35, v30, v30
	v_add_f32_e32 v34, v34, v35
	v_mul_f32_e32 v35, v25, v25
	v_fmac_f32_e32 v35, v24, v24
	v_cvt_pk_bf16_f32 v28, v28, v29
	v_cvt_pk_bf16_f32 v29, v30, v31
	v_cvt_pk_bf16_f32 v30, v24, v25
	v_mul_f32_e32 v24, v21, v21
	v_mul_f32_e32 v25, v23, v23
	v_fmac_f32_e32 v24, v20, v20
	v_fmac_f32_e32 v25, v22, v22
	v_add_f32_e32 v24, v24, v25
	v_mul_f32_e32 v25, v17, v17
	v_fmac_f32_e32 v25, v16, v16
	v_add_f32_e32 v34, v34, v35
	v_mul_f32_e32 v35, v27, v27
	v_add_f32_e32 v24, v24, v25
	v_mul_f32_e32 v25, v19, v19
	v_fmac_f32_e32 v35, v26, v26
	v_fmac_f32_e32 v25, v18, v18
	v_add_f32_e32 v34, v35, v34
	v_add_f32_e32 v24, v25, v24
	v_add_f32_e32 v24, v34, v24
	ds_bpermute_b32 v25, v154, v24
	s_mov_b64 s[6:7], 0x50000
	s_waitcnt lgkmcnt(0)
	v_lshl_add_u64 v[32:33], v[142:143], 0, s[6:7]
	v_cvt_pk_bf16_f32 v31, v26, v27
	s_mov_b64 s[6:7], 0x50100
	global_store_dwordx4 v[32:33], v[28:31], off sc0 sc1
	s_nop 1
	v_cvt_pk_bf16_f32 v20, v20, v21
	v_cvt_pk_bf16_f32 v21, v22, v23
	v_cvt_pk_bf16_f32 v22, v16, v17
	v_add_f32_e32 v16, v24, v25
	ds_bpermute_b32 v17, v155, v16
	v_cvt_pk_bf16_f32 v23, v18, v19
	v_lshl_add_u64 v[18:19], v[142:143], 0, s[6:7]
	global_store_dwordx4 v[18:19], v[20:23], off sc0 sc1
	s_nop 1
	s_and_saveexec_b64 s[6:7], s[0:1]
	s_cbranch_execz .LBB0_1273
	s_mul_i32 s8, s10, 0x43000
	s_ashr_i32 s9, s8, 31
	s_waitcnt lgkmcnt(0)
	v_add_f32_e32 v18, v16, v17
	v_lshl_add_u64 v[16:17], s[8:9], 0, v[112:113]
	s_mul_i32 s56, s33, 0x10c00
	v_lshl_add_u64 v[16:17], v[16:17], 0, s[56:57]
	s_mov_b64 s[8:9], 0x280
	v_lshl_add_u64 v[16:17], v[16:17], 0, s[8:9]
	global_store_dword v[16:17], v18, off sc0 sc1
	s_nop 1
.LBB0_1273:
	s_or_b64 exec, exec, s[6:7]
	v_mul_f32_e32 v18, v13, v13
	v_mul_f32_e32 v19, v15, v15
	v_fmac_f32_e32 v18, v12, v12
	v_fmac_f32_e32 v19, v14, v14
	v_add_f32_e32 v18, v18, v19
	v_mul_f32_e32 v19, v9, v9
	v_fmac_f32_e32 v19, v8, v8
	v_cvt_pk_bf16_f32 v12, v12, v13
	v_cvt_pk_bf16_f32 v13, v14, v15
	v_cvt_pk_bf16_f32 v14, v8, v9
	v_mul_f32_e32 v8, v5, v5
	v_mul_f32_e32 v9, v7, v7
	v_fmac_f32_e32 v8, v4, v4
	v_fmac_f32_e32 v9, v6, v6
	v_add_f32_e32 v8, v8, v9
	v_mul_f32_e32 v9, v1, v1
	v_fmac_f32_e32 v9, v0, v0
	v_add_f32_e32 v18, v18, v19
	v_mul_f32_e32 v19, v11, v11
	v_add_f32_e32 v8, v8, v9
	v_mul_f32_e32 v9, v3, v3
	v_fmac_f32_e32 v19, v10, v10
	v_fmac_f32_e32 v9, v2, v2
	v_add_f32_e32 v18, v19, v18
	v_add_f32_e32 v8, v9, v8
	v_add_f32_e32 v8, v18, v8
	ds_bpermute_b32 v9, v154, v8
	s_mov_b64 s[6:7], 0x58000
	s_waitcnt lgkmcnt(0)
	v_lshl_add_u64 v[16:17], v[142:143], 0, s[6:7]
	v_cvt_pk_bf16_f32 v15, v10, v11
	s_mov_b64 s[6:7], 0x58100
	global_store_dwordx4 v[16:17], v[12:15], off sc0 sc1
	s_nop 1
	v_cvt_pk_bf16_f32 v4, v4, v5
	v_cvt_pk_bf16_f32 v5, v6, v7
	v_cvt_pk_bf16_f32 v6, v0, v1
	v_add_f32_e32 v0, v8, v9
	ds_bpermute_b32 v1, v155, v0
	v_cvt_pk_bf16_f32 v7, v2, v3
	v_lshl_add_u64 v[2:3], v[142:143], 0, s[6:7]
	global_store_dwordx4 v[2:3], v[4:7], off sc0 sc1
	s_nop 1
	s_and_saveexec_b64 s[6:7], s[0:1]
	s_cbranch_execz .LBB0_1275
	s_mul_i32 s8, s10, 0x43000
	s_ashr_i32 s9, s8, 31
	s_waitcnt lgkmcnt(0)
	v_add_f32_e32 v2, v0, v1
	v_lshl_add_u64 v[0:1], s[8:9], 0, v[112:113]
	s_mul_i32 s56, s33, 0x10c00
	v_lshl_add_u64 v[0:1], v[0:1], 0, s[56:57]
	s_mov_b64 s[8:9], 0x2c0
	v_lshl_add_u64 v[0:1], v[0:1], 0, s[8:9]
	global_store_dword v[0:1], v2, off sc0 sc1
	s_nop 1

.LBB0_1350:
	v_mov_b32_e32 v32, v152
	v_readlane_b32 s68, v254, 4
	v_ashrrev_i32_e32 v33, 31, v32
	s_waitcnt lgkmcnt(0)
	v_lshlrev_b64 v[0:1], 4, v[32:33]
	v_readlane_b32 s70, v254, 6
	v_readlane_b32 s71, v254, 7
	s_mov_b64 s[0:1], 0x1000
	v_readlane_b32 s69, v254, 5
	v_lshl_add_u64 v[20:21], s[70:71], 0, v[0:1]
	v_lshl_add_u64 v[0:1], s[64:65], 0, v[0:1]
	v_add_co_u32_e32 v24, vcc, 0x1000, v0
	v_lshl_add_u64 v[28:29], v[0:1], 0, s[0:1]
	s_nop 0
	v_addc_co_u32_e32 v25, vcc, 0, v1, vcc
	global_load_dwordx4 v[0:3], v[20:21], off
	global_load_dwordx4 v[4:7], v[20:21], off offset:1024
	global_load_dwordx4 v[8:11], v[28:29], off offset:1024
	global_load_dwordx4 v[12:15], v[28:29], off offset:2048
	global_load_dwordx4 v[16:19], v[20:21], off offset:2048
	s_nop 0
	global_load_dwordx4 v[20:23], v[20:21], off offset:3072
	s_nop 0
	global_load_dwordx4 v[24:27], v[24:25], off
	s_nop 0
	global_load_dwordx4 v[28:31], v[28:29], off offset:3072
	s_add_u32 s0, s24, 0x5c000
	v_writelane_b32 v255, s0, 2
	s_addc_u32 s0, s25, 0
	v_writelane_b32 v255, s0, 3
	v_readlane_b32 s0, v254, 60
	v_readlane_b32 s72, v254, 8
	v_readlane_b32 s73, v254, 9
	v_readlane_b32 s74, v254, 10
	v_readlane_b32 s75, v254, 11
	v_readlane_b32 s78, v254, 14
	v_readlane_b32 s79, v254, 15
	s_add_u32 s58, s24, 0x74300
	v_readlane_b32 s1, v254, 61
	v_lshlrev_b64 v[40:41], 3, v[32:33]
	s_mov_b32 s57, 0
	s_addc_u32 s59, s25, 0
	v_cmp_gt_i32_e64 s[14:15], 16, v32
	v_mul_u32_u24_e32 v34, 0x10c00, v32
	v_mov_b32_e32 v35, 0
	v_lshl_add_u64 v[34:35], v[34:35], 0, s[0:1]
	v_lshl_add_u64 v[36:37], s[30:31], 0, v[40:41]
	v_lshl_add_u64 v[38:39], s[20:21], 0, v[40:41]
	v_lshl_add_u64 v[40:41], s[24:25], 0, v[40:41]
	s_mov_b32 s3, -1
	v_mov_b32_e32 v43, 0
	s_add_i32 s96, 0, 0x20080
	s_mov_b64 s[62:63], 0x800
	s_mov_b64 s[64:65], 0xa00
	s_mov_b64 s[68:69], 0xc00
	s_mov_b64 s[70:71], 0xe00
	v_mov_b32_e32 v146, 0x358637bd
	s_mov_b32 s97, 0x800000
	v_mov_b32_e32 v147, 0x160
	s_mov_b64 s[72:73], 0x200
	s_mov_b64 s[74:75], 0x400
	s_mov_b64 s[78:79], 0x600
	v_readlane_b32 s76, v254, 12
	v_readlane_b32 s77, v254, 13
	v_readlane_b32 s80, v254, 16
	v_readlane_b32 s81, v254, 17
	v_readlane_b32 s82, v254, 18
	v_readlane_b32 s83, v254, 19
	s_branch .LBB0_1354

.LBB0_1419:
	s_mov_b32 s81, s57
	v_mov_b32_e32 v42, 0
	s_and_saveexec_b64 s[10:11], s[14:15]
	s_cbranch_execz .LBB0_1421
	s_lshl_b64 s[12:13], s[80:81], 2
	v_lshl_add_u64 v[44:45], v[34:35], 0, s[12:13]
	global_load_dword v42, v[44:45], off

.LBB0_1428:
	v_mov_b32_e32 v42, 0
	s_and_saveexec_b64 s[10:11], s[14:15]
	s_cbranch_execz .LBB0_1430
	s_lshl_b64 s[12:13], s[56:57], 2
	v_lshl_add_u64 v[44:45], v[34:35], 0, s[12:13]
	global_load_dword v42, v[44:45], off

.LBB0_1446:
	v_mov_b32_e32 v42, 0
	s_and_saveexec_b64 s[8:9], s[14:15]
	s_cbranch_execz .LBB0_1351
	s_lshl_b64 s[10:11], s[56:57], 2
	v_lshl_add_u64 v[44:45], v[34:35], 0, s[10:11]
	global_load_dword v42, v[44:45], off
	s_branch .LBB0_1351

.LBB0_1876:
	v_mul_f32_e32 v157, v125, v125
	v_mul_f32_e32 v158, v127, v127
	v_fmac_f32_e32 v157, v124, v124
	v_fmac_f32_e32 v158, v126, v126
	v_add_f32_e32 v157, v157, v158
	v_mul_f32_e32 v158, v121, v121
	v_fmac_f32_e32 v158, v120, v120
	v_cvt_pk_bf16_f32 v124, v124, v125
	v_cvt_pk_bf16_f32 v125, v126, v127
	v_cvt_pk_bf16_f32 v126, v120, v121
	v_mul_f32_e32 v120, v117, v117
	v_mul_f32_e32 v121, v119, v119
	v_fmac_f32_e32 v120, v116, v116
	v_fmac_f32_e32 v121, v118, v118
	v_add_f32_e32 v120, v120, v121
	v_mul_f32_e32 v121, v113, v113
	v_fmac_f32_e32 v121, v112, v112
	v_add_f32_e32 v157, v157, v158
	v_mul_f32_e32 v158, v123, v123
	v_add_f32_e32 v120, v120, v121
	v_mul_f32_e32 v121, v115, v115
	v_fmac_f32_e32 v158, v122, v122
	v_fmac_f32_e32 v121, v114, v114
	v_add_f32_e32 v157, v158, v157
	v_add_f32_e32 v120, v121, v120
	v_lshl_add_u32 v144, s52, 8, v146
	v_add_f32_e32 v120, v157, v120
	v_ashrrev_i32_e32 v145, 31, v144
	ds_bpermute_b32 v121, v154, v120
	v_lshlrev_b64 v[142:143], 11, v[144:145]
	s_lshl_b32 s6, s54, 8
	v_lshl_add_u64 v[142:143], s[20:21], 0, v[142:143]
	s_ashr_i32 s7, s6, 31
	v_lshl_add_u64 v[142:143], s[6:7], 1, v[142:143]
	s_mov_b32 s65, s57
	v_lshl_add_u64 v[142:143], v[142:143], 0, s[64:65]
	v_lshl_add_u64 v[142:143], v[142:143], 0, v[136:137]
	v_cvt_pk_bf16_f32 v127, v122, v123
	s_mov_b64 s[6:7], 0x100
	global_store_dwordx4 v[142:143], v[124:127], off sc0 sc1
	s_nop 1
	v_cvt_pk_bf16_f32 v116, v116, v117
	v_cvt_pk_bf16_f32 v117, v118, v119
	v_cvt_pk_bf16_f32 v118, v112, v113
	v_cvt_pk_bf16_f32 v119, v114, v115
	s_waitcnt lgkmcnt(0)
	v_add_f32_e32 v114, v120, v121
	ds_bpermute_b32 v115, v155, v114
	v_lshl_add_u64 v[112:113], v[142:143], 0, s[6:7]
	global_store_dwordx4 v[112:113], v[116:119], off sc0 sc1
	s_nop 1
	v_readlane_b32 s6, v254, 60
	v_lshlrev_b64 v[112:113], 2, v[144:145]
	v_readlane_b32 s7, v254, 61
	s_nop 1
	v_lshl_add_u64 v[112:113], s[6:7], 0, v[112:113]
	s_and_saveexec_b64 s[6:7], s[0:1]
	s_cbranch_execz .LBB0_1878
	s_mul_i32 s8, s54, 0x43000
	s_ashr_i32 s9, s8, 31
	s_waitcnt lgkmcnt(0)
	v_add_f32_e32 v116, v114, v115
	v_lshl_add_u64 v[114:115], s[8:9], 0, v[112:113]
	s_mul_i32 s56, s17, 0x10c00
	v_lshl_add_u64 v[114:115], v[114:115], 0, s[56:57]
	global_store_dword v[114:115], v116, off sc0 sc1
	s_nop 1
.LBB0_1878:
	s_or_b64 exec, exec, s[6:7]
	v_mul_f32_e32 v116, v109, v109
	v_mul_f32_e32 v117, v111, v111
	v_fmac_f32_e32 v116, v108, v108
	v_fmac_f32_e32 v117, v110, v110
	v_add_f32_e32 v116, v116, v117
	v_mul_f32_e32 v117, v105, v105
	v_fmac_f32_e32 v117, v104, v104
	v_cvt_pk_bf16_f32 v108, v108, v109
	v_cvt_pk_bf16_f32 v109, v110, v111
	v_cvt_pk_bf16_f32 v110, v104, v105
	v_mul_f32_e32 v104, v101, v101
	v_mul_f32_e32 v105, v103, v103
	v_fmac_f32_e32 v104, v100, v100
	v_fmac_f32_e32 v105, v102, v102
	v_add_f32_e32 v104, v104, v105
	v_mul_f32_e32 v105, v97, v97
	v_fmac_f32_e32 v105, v96, v96
	v_add_f32_e32 v116, v116, v117
	v_mul_f32_e32 v117, v107, v107
	v_add_f32_e32 v104, v104, v105
	v_mul_f32_e32 v105, v99, v99
	v_fmac_f32_e32 v117, v106, v106
	v_fmac_f32_e32 v105, v98, v98
	v_add_f32_e32 v116, v117, v116
	v_add_f32_e32 v104, v105, v104
	v_add_f32_e32 v104, v116, v104
	ds_bpermute_b32 v105, v154, v104
	s_mov_b64 s[6:7], 0x8000
	s_waitcnt lgkmcnt(0)
	v_lshl_add_u64 v[114:115], v[142:143], 0, s[6:7]
	v_cvt_pk_bf16_f32 v111, v106, v107
	s_mov_b64 s[6:7], 0x8100
	global_store_dwordx4 v[114:115], v[108:111], off sc0 sc1
	s_nop 1
	v_cvt_pk_bf16_f32 v100, v100, v101
	v_cvt_pk_bf16_f32 v101, v102, v103
	v_cvt_pk_bf16_f32 v102, v96, v97
	v_add_f32_e32 v96, v104, v105
	ds_bpermute_b32 v97, v155, v96
	v_cvt_pk_bf16_f32 v103, v98, v99
	v_lshl_add_u64 v[98:99], v[142:143], 0, s[6:7]
	global_store_dwordx4 v[98:99], v[100:103], off sc0 sc1
	s_nop 1
	s_and_saveexec_b64 s[6:7], s[0:1]
	s_cbranch_execz .LBB0_1880
	s_waitcnt lgkmcnt(0)
	v_add_f32_e32 v98, v96, v97
	v_or_b32_e32 v96, 16, v144
	v_ashrrev_i32_e32 v97, 31, v96
	v_readlane_b32 s8, v254, 60
	v_lshlrev_b64 v[96:97], 2, v[96:97]
	v_readlane_b32 s9, v254, 61
	s_mul_i32 s56, s17, 0x10c00
	s_nop 0
	v_lshl_add_u64 v[96:97], s[8:9], 0, v[96:97]
	s_mul_i32 s8, s54, 0x43000
	s_ashr_i32 s9, s8, 31
	v_lshl_add_u64 v[96:97], s[8:9], 0, v[96:97]
	v_lshl_add_u64 v[96:97], v[96:97], 0, s[56:57]
	global_store_dword v[96:97], v98, off sc0 sc1
	s_nop 1
.LBB0_1880:
	s_or_b64 exec, exec, s[6:7]
	v_mul_f32_e32 v98, v93, v93
	v_mul_f32_e32 v99, v95, v95
	v_fmac_f32_e32 v98, v92, v92
	v_fmac_f32_e32 v99, v94, v94
	v_add_f32_e32 v98, v98, v99
	v_mul_f32_e32 v99, v89, v89
	v_fmac_f32_e32 v99, v88, v88
	v_cvt_pk_bf16_f32 v92, v92, v93
	v_cvt_pk_bf16_f32 v93, v94, v95
	v_cvt_pk_bf16_f32 v94, v88, v89
	v_mul_f32_e32 v88, v85, v85
	v_mul_f32_e32 v89, v87, v87
	v_fmac_f32_e32 v88, v84, v84
	v_fmac_f32_e32 v89, v86, v86
	v_add_f32_e32 v88, v88, v89
	v_mul_f32_e32 v89, v81, v81
	v_fmac_f32_e32 v89, v80, v80
	v_add_f32_e32 v98, v98, v99
	v_mul_f32_e32 v99, v91, v91
	v_add_f32_e32 v88, v88, v89
	v_mul_f32_e32 v89, v83, v83
	v_fmac_f32_e32 v99, v90, v90
	v_fmac_f32_e32 v89, v82, v82
	v_add_f32_e32 v98, v99, v98
	v_add_f32_e32 v88, v89, v88
	v_add_f32_e32 v88, v98, v88
	ds_bpermute_b32 v89, v154, v88
	s_mov_b64 s[6:7], 0x10000
	s_waitcnt lgkmcnt(0)
	v_lshl_add_u64 v[96:97], v[142:143], 0, s[6:7]
	v_cvt_pk_bf16_f32 v95, v90, v91
	s_mov_b64 s[6:7], 0x10100
	global_store_dwordx4 v[96:97], v[92:95], off sc0 sc1
	s_nop 1
	v_cvt_pk_bf16_f32 v84, v84, v85
	v_cvt_pk_bf16_f32 v85, v86, v87
	v_cvt_pk_bf16_f32 v86, v80, v81
	v_add_f32_e32 v80, v88, v89
	ds_bpermute_b32 v81, v155, v80
	v_cvt_pk_bf16_f32 v87, v82, v83
	v_lshl_add_u64 v[82:83], v[142:143], 0, s[6:7]
	global_store_dwordx4 v[82:83], v[84:87], off sc0 sc1
	s_nop 1
	s_and_saveexec_b64 s[6:7], s[0:1]
	s_cbranch_execz .LBB0_1882
	s_waitcnt lgkmcnt(0)
	v_add_f32_e32 v82, v80, v81
	v_or_b32_e32 v80, 32, v144
	v_ashrrev_i32_e32 v81, 31, v80
	v_readlane_b32 s8, v254, 60
	v_lshlrev_b64 v[80:81], 2, v[80:81]
	v_readlane_b32 s9, v254, 61
	s_mul_i32 s56, s17, 0x10c00
	s_nop 0
	v_lshl_add_u64 v[80:81], s[8:9], 0, v[80:81]
	s_mul_i32 s8, s54, 0x43000
	s_ashr_i32 s9, s8, 31
	v_lshl_add_u64 v[80:81], s[8:9], 0, v[80:81]
	v_lshl_add_u64 v[80:81], v[80:81], 0, s[56:57]
	global_store_dword v[80:81], v82, off sc0 sc1
	s_nop 1
.LBB0_1882:
	s_or_b64 exec, exec, s[6:7]
	v_mul_f32_e32 v82, v77, v77
	v_mul_f32_e32 v83, v79, v79
	v_fmac_f32_e32 v82, v76, v76
	v_fmac_f32_e32 v83, v78, v78
	v_add_f32_e32 v82, v82, v83
	v_mul_f32_e32 v83, v73, v73
	v_fmac_f32_e32 v83, v72, v72
	v_cvt_pk_bf16_f32 v76, v76, v77
	v_cvt_pk_bf16_f32 v77, v78, v79
	v_cvt_pk_bf16_f32 v78, v72, v73
	v_mul_f32_e32 v72, v69, v69
	v_mul_f32_e32 v73, v71, v71
	v_fmac_f32_e32 v72, v68, v68
	v_fmac_f32_e32 v73, v70, v70
	v_add_f32_e32 v72, v72, v73
	v_mul_f32_e32 v73, v65, v65
	v_fmac_f32_e32 v73, v64, v64
	v_add_f32_e32 v82, v82, v83
	v_mul_f32_e32 v83, v75, v75
	v_add_f32_e32 v72, v72, v73
	v_mul_f32_e32 v73, v67, v67
	v_fmac_f32_e32 v83, v74, v74
	v_fmac_f32_e32 v73, v66, v66
	v_add_f32_e32 v82, v83, v82
	v_add_f32_e32 v72, v73, v72
	v_add_f32_e32 v72, v82, v72
	ds_bpermute_b32 v73, v154, v72
	s_mov_b64 s[6:7], 0x18000
	s_waitcnt lgkmcnt(0)
	v_lshl_add_u64 v[80:81], v[142:143], 0, s[6:7]
	v_cvt_pk_bf16_f32 v79, v74, v75
	s_mov_b64 s[6:7], 0x18100
	global_store_dwordx4 v[80:81], v[76:79], off sc0 sc1
	s_nop 1
	v_cvt_pk_bf16_f32 v68, v68, v69
	v_cvt_pk_bf16_f32 v69, v70, v71
	v_cvt_pk_bf16_f32 v70, v64, v65
	v_add_f32_e32 v64, v72, v73
	ds_bpermute_b32 v65, v155, v64
	v_cvt_pk_bf16_f32 v71, v66, v67
	v_lshl_add_u64 v[66:67], v[142:143], 0, s[6:7]
	global_store_dwordx4 v[66:67], v[68:71], off sc0 sc1
	s_nop 1
	s_and_saveexec_b64 s[6:7], s[0:1]
	s_cbranch_execz .LBB0_1884
	s_waitcnt lgkmcnt(0)
	v_add_f32_e32 v66, v64, v65
	v_or_b32_e32 v64, 48, v144
	v_ashrrev_i32_e32 v65, 31, v64
	v_readlane_b32 s8, v254, 60
	v_lshlrev_b64 v[64:65], 2, v[64:65]
	v_readlane_b32 s9, v254, 61
	s_mul_i32 s56, s17, 0x10c00
	s_nop 0
	v_lshl_add_u64 v[64:65], s[8:9], 0, v[64:65]
	s_mul_i32 s8, s54, 0x43000
	s_ashr_i32 s9, s8, 31
	v_lshl_add_u64 v[64:65], s[8:9], 0, v[64:65]
	v_lshl_add_u64 v[64:65], v[64:65], 0, s[56:57]
	global_store_dword v[64:65], v66, off sc0 sc1
	s_nop 1
.LBB0_1884:
	s_or_b64 exec, exec, s[6:7]
	v_mul_f32_e32 v66, v61, v61
	v_mul_f32_e32 v67, v63, v63
	v_fmac_f32_e32 v66, v60, v60
	v_fmac_f32_e32 v67, v62, v62
	v_add_f32_e32 v66, v66, v67
	v_mul_f32_e32 v67, v57, v57
	v_fmac_f32_e32 v67, v56, v56
	v_cvt_pk_bf16_f32 v60, v60, v61
	v_cvt_pk_bf16_f32 v61, v62, v63
	v_cvt_pk_bf16_f32 v62, v56, v57
	v_mul_f32_e32 v56, v53, v53
	v_mul_f32_e32 v57, v55, v55
	v_fmac_f32_e32 v56, v52, v52
	v_fmac_f32_e32 v57, v54, v54
	v_add_f32_e32 v56, v56, v57
	v_mul_f32_e32 v57, v49, v49
	v_fmac_f32_e32 v57, v48, v48
	v_add_f32_e32 v66, v66, v67
	v_mul_f32_e32 v67, v59, v59
	v_add_f32_e32 v56, v56, v57
	v_mul_f32_e32 v57, v51, v51
	v_fmac_f32_e32 v67, v58, v58
	v_fmac_f32_e32 v57, v50, v50
	v_add_f32_e32 v66, v67, v66
	v_add_f32_e32 v56, v57, v56
	v_add_f32_e32 v56, v66, v56
	ds_bpermute_b32 v57, v154, v56
	s_mov_b64 s[6:7], 0x40000
	s_waitcnt lgkmcnt(0)
	v_lshl_add_u64 v[64:65], v[142:143], 0, s[6:7]
	v_cvt_pk_bf16_f32 v63, v58, v59
	s_mov_b64 s[6:7], 0x40100
	global_store_dwordx4 v[64:65], v[60:63], off sc0 sc1
	s_nop 1
	v_cvt_pk_bf16_f32 v52, v52, v53
	v_cvt_pk_bf16_f32 v53, v54, v55
	v_cvt_pk_bf16_f32 v54, v48, v49
	v_add_f32_e32 v48, v56, v57
	ds_bpermute_b32 v49, v155, v48
	v_cvt_pk_bf16_f32 v55, v50, v51
	v_lshl_add_u64 v[50:51], v[142:143], 0, s[6:7]
	global_store_dwordx4 v[50:51], v[52:55], off sc0 sc1
	s_nop 1
	s_and_saveexec_b64 s[6:7], s[0:1]
	s_cbranch_execz .LBB0_1886
	s_mul_i32 s8, s54, 0x43000
	s_ashr_i32 s9, s8, 31
	s_waitcnt lgkmcnt(0)
	v_add_f32_e32 v50, v48, v49
	v_lshl_add_u64 v[48:49], s[8:9], 0, v[112:113]
	s_mul_i32 s56, s17, 0x10c00
	v_lshl_add_u64 v[48:49], v[48:49], 0, s[56:57]
	s_mov_b64 s[8:9], 0x200
	v_lshl_add_u64 v[48:49], v[48:49], 0, s[8:9]
	global_store_dword v[48:49], v50, off sc0 sc1
	s_nop 1
.LBB0_1886:
	s_or_b64 exec, exec, s[6:7]
	v_mul_f32_e32 v50, v45, v45
	v_mul_f32_e32 v51, v47, v47
	v_fmac_f32_e32 v50, v44, v44
	v_fmac_f32_e32 v51, v46, v46
	v_add_f32_e32 v50, v50, v51
	v_mul_f32_e32 v51, v41, v41
	v_fmac_f32_e32 v51, v40, v40
	v_cvt_pk_bf16_f32 v44, v44, v45
	v_cvt_pk_bf16_f32 v45, v46, v47
	v_cvt_pk_bf16_f32 v46, v40, v41
	v_mul_f32_e32 v40, v37, v37
	v_mul_f32_e32 v41, v39, v39
	v_fmac_f32_e32 v40, v36, v36
	v_fmac_f32_e32 v41, v38, v38
	v_add_f32_e32 v40, v40, v41
	v_mul_f32_e32 v41, v33, v33
	v_fmac_f32_e32 v41, v32, v32
	v_add_f32_e32 v50, v50, v51
	v_mul_f32_e32 v51, v43, v43
	v_add_f32_e32 v40, v40, v41
	v_mul_f32_e32 v41, v35, v35
	v_fmac_f32_e32 v51, v42, v42
	v_fmac_f32_e32 v41, v34, v34
	v_add_f32_e32 v50, v51, v50
	v_add_f32_e32 v40, v41, v40
	v_add_f32_e32 v40, v50, v40
	ds_bpermute_b32 v41, v154, v40
	s_mov_b64 s[6:7], 0x48000
	s_waitcnt lgkmcnt(0)
	v_lshl_add_u64 v[48:49], v[142:143], 0, s[6:7]
	v_cvt_pk_bf16_f32 v47, v42, v43
	s_mov_b64 s[6:7], 0x48100
	global_store_dwordx4 v[48:49], v[44:47], off sc0 sc1
	s_nop 1
	v_cvt_pk_bf16_f32 v36, v36, v37
	v_cvt_pk_bf16_f32 v37, v38, v39
	v_cvt_pk_bf16_f32 v38, v32, v33
	v_add_f32_e32 v32, v40, v41
	ds_bpermute_b32 v33, v155, v32
	v_cvt_pk_bf16_f32 v39, v34, v35
	v_lshl_add_u64 v[34:35], v[142:143], 0, s[6:7]
	global_store_dwordx4 v[34:35], v[36:39], off sc0 sc1
	s_nop 1
	s_and_saveexec_b64 s[6:7], s[0:1]
	s_cbranch_execz .LBB0_1888
	s_mul_i32 s8, s54, 0x43000
	s_ashr_i32 s9, s8, 31
	s_waitcnt lgkmcnt(0)
	v_add_f32_e32 v34, v32, v33
	v_lshl_add_u64 v[32:33], s[8:9], 0, v[112:113]
	s_mul_i32 s56, s17, 0x10c00
	v_lshl_add_u64 v[32:33], v[32:33], 0, s[56:57]
	s_mov_b64 s[8:9], 0x240
	v_lshl_add_u64 v[32:33], v[32:33], 0, s[8:9]
	global_store_dword v[32:33], v34, off sc0 sc1
	s_nop 1
.LBB0_1888:
	s_or_b64 exec, exec, s[6:7]
	v_mul_f32_e32 v34, v29, v29
	v_mul_f32_e32 v35, v31, v31
	v_fmac_f32_e32 v34, v28, v28
	v_fmac_f32_e32 v35, v30, v30
	v_add_f32_e32 v34, v34, v35
	v_mul_f32_e32 v35, v25, v25
	v_fmac_f32_e32 v35, v24, v24
	v_cvt_pk_bf16_f32 v28, v28, v29
	v_cvt_pk_bf16_f32 v29, v30, v31
	v_cvt_pk_bf16_f32 v30, v24, v25
	v_mul_f32_e32 v24, v21, v21
	v_mul_f32_e32 v25, v23, v23
	v_fmac_f32_e32 v24, v20, v20
	v_fmac_f32_e32 v25, v22, v22
	v_add_f32_e32 v24, v24, v25
	v_mul_f32_e32 v25, v17, v17
	v_fmac_f32_e32 v25, v16, v16
	v_add_f32_e32 v34, v34, v35
	v_mul_f32_e32 v35, v27, v27
	v_add_f32_e32 v24, v24, v25
	v_mul_f32_e32 v25, v19, v19
	v_fmac_f32_e32 v35, v26, v26
	v_fmac_f32_e32 v25, v18, v18
	v_add_f32_e32 v34, v35, v34
	v_add_f32_e32 v24, v25, v24
	v_add_f32_e32 v24, v34, v24
	ds_bpermute_b32 v25, v154, v24
	s_mov_b64 s[6:7], 0x50000
	s_waitcnt lgkmcnt(0)
	v_lshl_add_u64 v[32:33], v[142:143], 0, s[6:7]
	v_cvt_pk_bf16_f32 v31, v26, v27
	s_mov_b64 s[6:7], 0x50100
	global_store_dwordx4 v[32:33], v[28:31], off sc0 sc1
	s_nop 1
	v_cvt_pk_bf16_f32 v20, v20, v21
	v_cvt_pk_bf16_f32 v21, v22, v23
	v_cvt_pk_bf16_f32 v22, v16, v17
	v_add_f32_e32 v16, v24, v25
	ds_bpermute_b32 v17, v155, v16
	v_cvt_pk_bf16_f32 v23, v18, v19
	v_lshl_add_u64 v[18:19], v[142:143], 0, s[6:7]
	global_store_dwordx4 v[18:19], v[20:23], off sc0 sc1
	s_nop 1
	s_and_saveexec_b64 s[6:7], s[0:1]
	s_cbranch_execz .LBB0_1890
	s_mul_i32 s8, s54, 0x43000
	s_ashr_i32 s9, s8, 31
	s_waitcnt lgkmcnt(0)
	v_add_f32_e32 v18, v16, v17
	v_lshl_add_u64 v[16:17], s[8:9], 0, v[112:113]
	s_mul_i32 s56, s17, 0x10c00
	v_lshl_add_u64 v[16:17], v[16:17], 0, s[56:57]
	s_mov_b64 s[8:9], 0x280
	v_lshl_add_u64 v[16:17], v[16:17], 0, s[8:9]
	global_store_dword v[16:17], v18, off sc0 sc1
	s_nop 1
.LBB0_1890:
	s_or_b64 exec, exec, s[6:7]
	v_mul_f32_e32 v18, v13, v13
	v_mul_f32_e32 v19, v15, v15
	v_fmac_f32_e32 v18, v12, v12
	v_fmac_f32_e32 v19, v14, v14
	v_add_f32_e32 v18, v18, v19
	v_mul_f32_e32 v19, v9, v9
	v_fmac_f32_e32 v19, v8, v8
	v_cvt_pk_bf16_f32 v12, v12, v13
	v_cvt_pk_bf16_f32 v13, v14, v15
	v_cvt_pk_bf16_f32 v14, v8, v9
	v_mul_f32_e32 v8, v5, v5
	v_mul_f32_e32 v9, v7, v7
	v_fmac_f32_e32 v8, v4, v4
	v_fmac_f32_e32 v9, v6, v6
	v_add_f32_e32 v8, v8, v9
	v_mul_f32_e32 v9, v1, v1
	v_fmac_f32_e32 v9, v0, v0
	v_add_f32_e32 v18, v18, v19
	v_mul_f32_e32 v19, v11, v11
	v_add_f32_e32 v8, v8, v9
	v_mul_f32_e32 v9, v3, v3
	v_fmac_f32_e32 v19, v10, v10
	v_fmac_f32_e32 v9, v2, v2
	v_add_f32_e32 v18, v19, v18
	v_add_f32_e32 v8, v9, v8
	v_add_f32_e32 v8, v18, v8
	ds_bpermute_b32 v9, v154, v8
	s_mov_b64 s[6:7], 0x58000
	s_waitcnt lgkmcnt(0)
	v_lshl_add_u64 v[16:17], v[142:143], 0, s[6:7]
	v_cvt_pk_bf16_f32 v15, v10, v11
	s_mov_b64 s[6:7], 0x58100
	global_store_dwordx4 v[16:17], v[12:15], off sc0 sc1
	s_nop 1
	v_cvt_pk_bf16_f32 v4, v4, v5
	v_cvt_pk_bf16_f32 v5, v6, v7
	v_cvt_pk_bf16_f32 v6, v0, v1
	v_add_f32_e32 v0, v8, v9
	ds_bpermute_b32 v1, v155, v0
	v_cvt_pk_bf16_f32 v7, v2, v3
	v_lshl_add_u64 v[2:3], v[142:143], 0, s[6:7]
	global_store_dwordx4 v[2:3], v[4:7], off sc0 sc1
	s_nop 1
	s_and_saveexec_b64 s[6:7], s[0:1]
	s_cbranch_execz .LBB0_1892
	s_mul_i32 s8, s54, 0x43000
	s_ashr_i32 s9, s8, 31
	s_waitcnt lgkmcnt(0)
	v_add_f32_e32 v2, v0, v1
	v_lshl_add_u64 v[0:1], s[8:9], 0, v[112:113]
	s_mul_i32 s56, s17, 0x10c00
	v_lshl_add_u64 v[0:1], v[0:1], 0, s[56:57]
	s_mov_b64 s[8:9], 0x2c0
	v_lshl_add_u64 v[0:1], v[0:1], 0, s[8:9]
	global_store_dword v[0:1], v2, off sc0 sc1
	s_nop 1

.LBB0_1963:
	v_mov_b32_e32 v32, v152
	s_mov_b64 s[0:1], 0x1000
	v_ashrrev_i32_e32 v33, 31, v32
	s_waitcnt lgkmcnt(0)
	v_lshlrev_b64 v[0:1], 4, v[32:33]
	v_lshl_add_u64 v[2:3], s[66:67], 0, v[0:1]
	v_readlane_b32 s52, v254, 4
	v_readlane_b32 s53, v254, 5
	v_lshl_add_u64 v[34:35], v[2:3], 0, s[0:1]
	v_readlane_b32 s54, v254, 6
	v_lshl_add_u64 v[4:5], s[52:53], 0, v[0:1]
	v_add_co_u32_e32 v0, vcc, 0x1000, v2
	v_lshl_add_u64 v[36:37], v[4:5], 0, s[0:1]
	s_nop 0
	v_addc_co_u32_e32 v1, vcc, 0, v3, vcc
	v_add_co_u32_e32 v4, vcc, 0x1000, v4
	global_load_dwordx4 v[0:3], v[0:1], off
	s_nop 0
	v_addc_co_u32_e32 v5, vcc, 0, v5, vcc
	global_load_dwordx4 v[4:7], v[4:5], off
	s_nop 0
	global_load_dwordx4 v[8:11], v[34:35], off offset:1024
	global_load_dwordx4 v[12:15], v[34:35], off offset:2048
	global_load_dwordx4 v[16:19], v[36:37], off offset:1024
	global_load_dwordx4 v[20:23], v[36:37], off offset:2048
	global_load_dwordx4 v[24:27], v[34:35], off offset:3072
	global_load_dwordx4 v[28:31], v[36:37], off offset:3072
	s_add_u32 s0, s24, 0x4c000
	v_readlane_b32 s55, v254, 7
	v_readlane_b32 s56, v254, 8
	v_readlane_b32 s57, v254, 9
	v_readlane_b32 s58, v254, 10
	v_readlane_b32 s59, v254, 11
	v_readlane_b32 s60, v254, 12
	v_readlane_b32 s61, v254, 13
	v_readlane_b32 s62, v254, 14
	v_readlane_b32 s63, v254, 15
	v_readlane_b32 s64, v254, 16
	v_readlane_b32 s65, v254, 17
	v_readlane_b32 s66, v254, 18
	v_readlane_b32 s67, v254, 19
	v_writelane_b32 v254, s0, 47
	s_addc_u32 s0, s25, 0
	v_writelane_b32 v255, s0, 2
	v_readlane_b32 s0, v254, 60
	s_add_u32 s36, s24, 0x74500
	v_readlane_b32 s1, v254, 61
	v_lshlrev_b64 v[40:41], 3, v[32:33]
	s_mov_b32 s15, 0
	s_addc_u32 s37, s25, 0
	v_cmp_gt_i32_e64 s[8:9], 16, v32
	v_mul_u32_u24_e32 v34, 0x10c00, v32
	v_mov_b32_e32 v35, 0
	v_lshl_add_u64 v[34:35], v[34:35], 0, s[0:1]
	v_lshl_add_u64 v[36:37], s[30:31], 0, v[40:41]
	v_lshl_add_u64 v[38:39], s[20:21], 0, v[40:41]
	v_lshl_add_u64 v[40:41], s[24:25], 0, v[40:41]
	s_mov_b32 s3, -1
	v_mov_b32_e32 v43, 0
	s_add_i32 s90, 0, 0x20080
	s_mov_b64 s[40:41], 0x800
	s_mov_b64 s[52:53], 0xa00
	s_mov_b64 s[54:55], 0xc00
	s_mov_b64 s[56:57], 0xe00
	v_mov_b32_e32 v90, 0x358637bd
	s_mov_b32 s91, 0x800000
	s_mov_b64 s[58:59], 0x200
	s_mov_b64 s[60:61], 0x400
	s_mov_b64 s[62:63], 0x600
	v_mov_b32_e32 v91, 0x80
	s_branch .LBB0_1967

.LBB0_2032:
	s_mov_b32 s65, s15
	v_mov_b32_e32 v42, 0
	s_and_saveexec_b64 s[38:39], s[8:9]
	s_cbranch_execz .LBB0_2034
	s_lshl_b64 s[12:13], s[64:65], 2
	v_lshl_add_u64 v[44:45], v[34:35], 0, s[12:13]
	global_load_dword v42, v[44:45], off

.LBB0_2041:
	v_mov_b32_e32 v42, 0
	s_and_saveexec_b64 s[38:39], s[8:9]
	s_cbranch_execz .LBB0_2043
	s_lshl_b64 s[12:13], s[14:15], 2
	v_lshl_add_u64 v[44:45], v[34:35], 0, s[12:13]
	global_load_dword v42, v[44:45], off

.LBB0_2059:
	v_mov_b32_e32 v42, 0
	s_and_saveexec_b64 s[10:11], s[8:9]
	s_cbranch_execz .LBB0_1964
	s_lshl_b64 s[12:13], s[14:15], 2
	v_lshl_add_u64 v[44:45], v[34:35], 0, s[12:13]
	global_load_dword v42, v[44:45], off
	s_branch .LBB0_1964

.LBB0_2267:
	s_mov_b64 s[34:35], 0x80
	s_and_b32 s48, s0, 3
	s_add_i32 m0, s17, 0x18000
	v_lshl_add_u64 v[6:7], v[6:7], 0, s[34:35]
	s_lshl_b32 s0, s1, 13
	s_lshl_b32 s9, s48, 5
	s_lshl_b32 s14, s48, 12
	s_waitcnt vmcnt(2)
	s_barrier
	global_load_lds_dwordx4 v[6:7], off
	v_lshl_add_u64 v[4:5], v[4:5], 0, s[34:35]
	s_add_i32 m0, s17, 0x1a000
	s_add_i32 s49, s17, 0x8000
	s_add_i32 s68, s17, 0xa000
	global_load_lds_dwordx4 v[4:5], off
	v_lshl_add_u64 v[0:1], v[0:1], 0, s[34:35]
	s_mov_b32 m0, s49
	s_add_u32 s6, s62, 0xb0080
	global_load_lds_dwordx4 v[0:1], off
	v_lshl_add_u64 v[0:1], v[2:3], 0, s[34:35]
	s_mov_b32 m0, s68
	s_addc_u32 s7, s63, 0
	global_load_lds_dwordx4 v[0:1], off
	s_add_i32 m0, s17, 0x1c000
	v_lshl_add_u64 v[0:1], s[6:7], 0, v[130:131]
	global_load_lds_dwordx4 v[0:1], off
	v_lshl_add_u64 v[0:1], s[6:7], 0, v[134:135]
	s_add_i32 m0, s17, 0x1e000
	v_and_b32_e32 v2, 15, v8
	global_load_lds_dwordx4 v[0:1], off
	v_bfe_u32 v1, v8, 4, 2
	v_lshlrev_b32_e32 v3, 4, v1
	v_lshl_or_b32 v146, s1, 6, v2
	v_lshl_or_b32 v2, v2, 6, v3
	v_lshlrev_b32_e32 v3, 2, v8
	v_and_b32_e32 v3, 32, v3
	s_waitcnt vmcnt(6)
	v_lshlrev_b32_e32 v0, 3, v1
	v_bitop3_b32 v4, v2, s0, v3 bitop3:0xde
	s_cmpk_lt_u32 s8, 0x100
	v_bitop3_b32 v147, v2, s14, v3 bitop3:0xde
	s_cselect_b64 s[36:37], -1, 0
	v_cmp_eq_u32_e64 s[0:1], 0, v1
	s_ashr_i32 s69, s26, 31
	s_ashr_i32 s70, s2, 31
	v_mov_b64_e32 v[138:139], 0x100
	v_mov_b64_e32 v[140:141], 0xff
	s_add_i32 s71, 0, 0x10000
	s_add_i32 s72, 0, 0x14000
	v_add_u32_e32 v156, 0, v4
	s_lshl_b32 s40, s9, 1
	v_lshlrev_b32_e32 v136, 1, v0
	s_mov_b64 s[50:51], 0x58000
	s_mov_b64 s[52:53], 0x58100
	s_mov_b64 s[54:55], 0x2c0
	s_mov_b32 s73, 0
	s_barrier
	s_branch .LBB0_2270

.LBB0_2304:
	v_mul_f32_e32 v157, v125, v125
	v_mul_f32_e32 v158, v127, v127
	v_fmac_f32_e32 v157, v124, v124
	v_fmac_f32_e32 v158, v126, v126
	v_add_f32_e32 v157, v157, v158
	v_mul_f32_e32 v158, v121, v121
	v_fmac_f32_e32 v158, v120, v120
	v_cvt_pk_bf16_f32 v124, v124, v125
	v_cvt_pk_bf16_f32 v125, v126, v127
	v_cvt_pk_bf16_f32 v126, v120, v121
	v_mul_f32_e32 v120, v117, v117
	v_mul_f32_e32 v121, v119, v119
	v_fmac_f32_e32 v120, v116, v116
	v_fmac_f32_e32 v121, v118, v118
	v_add_f32_e32 v120, v120, v121
	v_mul_f32_e32 v121, v113, v113
	v_fmac_f32_e32 v121, v112, v112
	v_add_f32_e32 v157, v157, v158
	v_mul_f32_e32 v158, v123, v123
	v_add_f32_e32 v120, v120, v121
	v_mul_f32_e32 v121, v115, v115
	v_fmac_f32_e32 v158, v122, v122
	v_fmac_f32_e32 v121, v114, v114
	v_add_f32_e32 v157, v158, v157
	v_add_f32_e32 v120, v121, v120
	v_lshl_add_u32 v144, s12, 8, v146
	v_add_f32_e32 v120, v157, v120
	v_ashrrev_i32_e32 v145, 31, v144
	ds_bpermute_b32 v121, v154, v120
	v_lshlrev_b64 v[142:143], 11, v[144:145]
	s_lshl_b32 s8, s13, 8
	v_lshl_add_u64 v[142:143], s[20:21], 0, v[142:143]
	s_ashr_i32 s9, s8, 31
	v_lshl_add_u64 v[142:143], s[8:9], 1, v[142:143]
	s_mov_b32 s41, s15
	v_lshl_add_u64 v[142:143], v[142:143], 0, s[40:41]
	v_lshl_add_u64 v[142:143], v[142:143], 0, v[136:137]
	v_cvt_pk_bf16_f32 v127, v122, v123
	s_mov_b64 s[8:9], 0x100
	global_store_dwordx4 v[142:143], v[124:127], off sc0 sc1
	s_nop 1
	v_cvt_pk_bf16_f32 v116, v116, v117
	v_cvt_pk_bf16_f32 v117, v118, v119
	v_cvt_pk_bf16_f32 v118, v112, v113
	v_cvt_pk_bf16_f32 v119, v114, v115
	s_waitcnt lgkmcnt(0)
	v_add_f32_e32 v114, v120, v121
	ds_bpermute_b32 v115, v155, v114
	v_lshl_add_u64 v[112:113], v[142:143], 0, s[8:9]
	global_store_dwordx4 v[112:113], v[116:119], off sc0 sc1
	s_nop 1
	v_readlane_b32 s8, v254, 60
	v_lshlrev_b64 v[112:113], 2, v[144:145]
	v_readlane_b32 s9, v254, 61
	s_nop 1
	v_lshl_add_u64 v[112:113], s[8:9], 0, v[112:113]
	s_and_saveexec_b64 s[8:9], s[0:1]
	s_cbranch_execz .LBB0_2306
	s_mul_i32 s18, s13, 0x43000
	s_ashr_i32 s19, s18, 31
	s_waitcnt lgkmcnt(0)
	v_add_f32_e32 v116, v114, v115
	v_lshl_add_u64 v[114:115], s[18:19], 0, v[112:113]
	s_mul_i32 s14, s48, 0x10c00
	v_lshl_add_u64 v[114:115], v[114:115], 0, s[14:15]
	global_store_dword v[114:115], v116, off sc0 sc1
	s_nop 1
.LBB0_2306:
	s_or_b64 exec, exec, s[8:9]
	v_mul_f32_e32 v116, v109, v109
	v_mul_f32_e32 v117, v111, v111
	v_fmac_f32_e32 v116, v108, v108
	v_fmac_f32_e32 v117, v110, v110
	v_add_f32_e32 v116, v116, v117
	v_mul_f32_e32 v117, v105, v105
	v_fmac_f32_e32 v117, v104, v104
	v_cvt_pk_bf16_f32 v108, v108, v109
	v_cvt_pk_bf16_f32 v109, v110, v111
	v_cvt_pk_bf16_f32 v110, v104, v105
	v_mul_f32_e32 v104, v101, v101
	v_mul_f32_e32 v105, v103, v103
	v_fmac_f32_e32 v104, v100, v100
	v_fmac_f32_e32 v105, v102, v102
	v_add_f32_e32 v104, v104, v105
	v_mul_f32_e32 v105, v97, v97
	v_fmac_f32_e32 v105, v96, v96
	v_add_f32_e32 v116, v116, v117
	v_mul_f32_e32 v117, v107, v107
	v_add_f32_e32 v104, v104, v105
	v_mul_f32_e32 v105, v99, v99
	v_fmac_f32_e32 v117, v106, v106
	v_fmac_f32_e32 v105, v98, v98
	v_add_f32_e32 v116, v117, v116
	v_add_f32_e32 v104, v105, v104
	v_add_f32_e32 v104, v116, v104
	ds_bpermute_b32 v105, v154, v104
	s_mov_b64 s[8:9], 0x8000
	s_waitcnt lgkmcnt(0)
	v_lshl_add_u64 v[114:115], v[142:143], 0, s[8:9]
	v_cvt_pk_bf16_f32 v111, v106, v107
	s_mov_b64 s[8:9], 0x8100
	global_store_dwordx4 v[114:115], v[108:111], off sc0 sc1
	s_nop 1
	v_cvt_pk_bf16_f32 v100, v100, v101
	v_cvt_pk_bf16_f32 v101, v102, v103
	v_cvt_pk_bf16_f32 v102, v96, v97
	v_add_f32_e32 v96, v104, v105
	ds_bpermute_b32 v97, v155, v96
	v_cvt_pk_bf16_f32 v103, v98, v99
	v_lshl_add_u64 v[98:99], v[142:143], 0, s[8:9]
	global_store_dwordx4 v[98:99], v[100:103], off sc0 sc1
	s_nop 1
	s_and_saveexec_b64 s[8:9], s[0:1]
	s_cbranch_execz .LBB0_2308
	s_waitcnt lgkmcnt(0)
	v_add_f32_e32 v98, v96, v97
	v_or_b32_e32 v96, 16, v144
	v_ashrrev_i32_e32 v97, 31, v96
	v_readlane_b32 s18, v254, 60
	v_lshlrev_b64 v[96:97], 2, v[96:97]
	v_readlane_b32 s19, v254, 61
	s_mul_i32 s14, s48, 0x10c00
	s_nop 0
	v_lshl_add_u64 v[96:97], s[18:19], 0, v[96:97]
	s_mul_i32 s18, s13, 0x43000
	s_ashr_i32 s19, s18, 31
	v_lshl_add_u64 v[96:97], s[18:19], 0, v[96:97]
	v_lshl_add_u64 v[96:97], v[96:97], 0, s[14:15]
	global_store_dword v[96:97], v98, off sc0 sc1
	s_nop 1
.LBB0_2308:
	s_or_b64 exec, exec, s[8:9]
	v_mul_f32_e32 v98, v93, v93
	v_mul_f32_e32 v99, v95, v95
	v_fmac_f32_e32 v98, v92, v92
	v_fmac_f32_e32 v99, v94, v94
	v_add_f32_e32 v98, v98, v99
	v_mul_f32_e32 v99, v89, v89
	v_fmac_f32_e32 v99, v88, v88
	v_cvt_pk_bf16_f32 v92, v92, v93
	v_cvt_pk_bf16_f32 v93, v94, v95
	v_cvt_pk_bf16_f32 v94, v88, v89
	v_mul_f32_e32 v88, v85, v85
	v_mul_f32_e32 v89, v87, v87
	v_fmac_f32_e32 v88, v84, v84
	v_fmac_f32_e32 v89, v86, v86
	v_add_f32_e32 v88, v88, v89
	v_mul_f32_e32 v89, v81, v81
	v_fmac_f32_e32 v89, v80, v80
	v_add_f32_e32 v98, v98, v99
	v_mul_f32_e32 v99, v91, v91
	v_add_f32_e32 v88, v88, v89
	v_mul_f32_e32 v89, v83, v83
	v_fmac_f32_e32 v99, v90, v90
	v_fmac_f32_e32 v89, v82, v82
	v_add_f32_e32 v98, v99, v98
	v_add_f32_e32 v88, v89, v88
	v_add_f32_e32 v88, v98, v88
	ds_bpermute_b32 v89, v154, v88
	s_mov_b64 s[8:9], 0x10000
	s_waitcnt lgkmcnt(0)
	v_lshl_add_u64 v[96:97], v[142:143], 0, s[8:9]
	v_cvt_pk_bf16_f32 v95, v90, v91
	s_mov_b64 s[8:9], 0x10100
	global_store_dwordx4 v[96:97], v[92:95], off sc0 sc1
	s_nop 1
	v_cvt_pk_bf16_f32 v84, v84, v85
	v_cvt_pk_bf16_f32 v85, v86, v87
	v_cvt_pk_bf16_f32 v86, v80, v81
	v_add_f32_e32 v80, v88, v89
	ds_bpermute_b32 v81, v155, v80
	v_cvt_pk_bf16_f32 v87, v82, v83
	v_lshl_add_u64 v[82:83], v[142:143], 0, s[8:9]
	global_store_dwordx4 v[82:83], v[84:87], off sc0 sc1
	s_nop 1
	s_and_saveexec_b64 s[8:9], s[0:1]
	s_cbranch_execz .LBB0_2310
	s_waitcnt lgkmcnt(0)
	v_add_f32_e32 v82, v80, v81
	v_or_b32_e32 v80, 32, v144
	v_ashrrev_i32_e32 v81, 31, v80
	v_readlane_b32 s18, v254, 60
	v_lshlrev_b64 v[80:81], 2, v[80:81]
	v_readlane_b32 s19, v254, 61
	s_mul_i32 s14, s48, 0x10c00
	s_nop 0
	v_lshl_add_u64 v[80:81], s[18:19], 0, v[80:81]
	s_mul_i32 s18, s13, 0x43000
	s_ashr_i32 s19, s18, 31
	v_lshl_add_u64 v[80:81], s[18:19], 0, v[80:81]
	v_lshl_add_u64 v[80:81], v[80:81], 0, s[14:15]
	global_store_dword v[80:81], v82, off sc0 sc1
	s_nop 1
.LBB0_2310:
	s_or_b64 exec, exec, s[8:9]
	v_mul_f32_e32 v82, v77, v77
	v_mul_f32_e32 v83, v79, v79
	v_fmac_f32_e32 v82, v76, v76
	v_fmac_f32_e32 v83, v78, v78
	v_add_f32_e32 v82, v82, v83
	v_mul_f32_e32 v83, v73, v73
	v_fmac_f32_e32 v83, v72, v72
	v_cvt_pk_bf16_f32 v76, v76, v77
	v_cvt_pk_bf16_f32 v77, v78, v79
	v_cvt_pk_bf16_f32 v78, v72, v73
	v_mul_f32_e32 v72, v69, v69
	v_mul_f32_e32 v73, v71, v71
	v_fmac_f32_e32 v72, v68, v68
	v_fmac_f32_e32 v73, v70, v70
	v_add_f32_e32 v72, v72, v73
	v_mul_f32_e32 v73, v65, v65
	v_fmac_f32_e32 v73, v64, v64
	v_add_f32_e32 v82, v82, v83
	v_mul_f32_e32 v83, v75, v75
	v_add_f32_e32 v72, v72, v73
	v_mul_f32_e32 v73, v67, v67
	v_fmac_f32_e32 v83, v74, v74
	v_fmac_f32_e32 v73, v66, v66
	v_add_f32_e32 v82, v83, v82
	v_add_f32_e32 v72, v73, v72
	v_add_f32_e32 v72, v82, v72
	ds_bpermute_b32 v73, v154, v72
	s_mov_b64 s[8:9], 0x18000
	s_waitcnt lgkmcnt(0)
	v_lshl_add_u64 v[80:81], v[142:143], 0, s[8:9]
	v_cvt_pk_bf16_f32 v79, v74, v75
	s_mov_b64 s[8:9], 0x18100
	global_store_dwordx4 v[80:81], v[76:79], off sc0 sc1
	s_nop 1
	v_cvt_pk_bf16_f32 v68, v68, v69
	v_cvt_pk_bf16_f32 v69, v70, v71
	v_cvt_pk_bf16_f32 v70, v64, v65
	v_add_f32_e32 v64, v72, v73
	ds_bpermute_b32 v65, v155, v64
	v_cvt_pk_bf16_f32 v71, v66, v67
	v_lshl_add_u64 v[66:67], v[142:143], 0, s[8:9]
	global_store_dwordx4 v[66:67], v[68:71], off sc0 sc1
	s_nop 1
	s_and_saveexec_b64 s[8:9], s[0:1]
	s_cbranch_execz .LBB0_2312
	s_waitcnt lgkmcnt(0)
	v_add_f32_e32 v66, v64, v65
	v_or_b32_e32 v64, 48, v144
	v_ashrrev_i32_e32 v65, 31, v64
	v_readlane_b32 s18, v254, 60
	v_lshlrev_b64 v[64:65], 2, v[64:65]
	v_readlane_b32 s19, v254, 61
	s_mul_i32 s14, s48, 0x10c00
	s_nop 0
	v_lshl_add_u64 v[64:65], s[18:19], 0, v[64:65]
	s_mul_i32 s18, s13, 0x43000
	s_ashr_i32 s19, s18, 31
	v_lshl_add_u64 v[64:65], s[18:19], 0, v[64:65]
	v_lshl_add_u64 v[64:65], v[64:65], 0, s[14:15]
	global_store_dword v[64:65], v66, off sc0 sc1
	s_nop 1
.LBB0_2312:
	s_or_b64 exec, exec, s[8:9]
	v_mul_f32_e32 v66, v61, v61
	v_mul_f32_e32 v67, v63, v63
	v_fmac_f32_e32 v66, v60, v60
	v_fmac_f32_e32 v67, v62, v62
	v_add_f32_e32 v66, v66, v67
	v_mul_f32_e32 v67, v57, v57
	v_fmac_f32_e32 v67, v56, v56
	v_cvt_pk_bf16_f32 v60, v60, v61
	v_cvt_pk_bf16_f32 v61, v62, v63
	v_cvt_pk_bf16_f32 v62, v56, v57
	v_mul_f32_e32 v56, v53, v53
	v_mul_f32_e32 v57, v55, v55
	v_fmac_f32_e32 v56, v52, v52
	v_fmac_f32_e32 v57, v54, v54
	v_add_f32_e32 v56, v56, v57
	v_mul_f32_e32 v57, v49, v49
	v_fmac_f32_e32 v57, v48, v48
	v_add_f32_e32 v66, v66, v67
	v_mul_f32_e32 v67, v59, v59
	v_add_f32_e32 v56, v56, v57
	v_mul_f32_e32 v57, v51, v51
	v_fmac_f32_e32 v67, v58, v58
	v_fmac_f32_e32 v57, v50, v50
	v_add_f32_e32 v66, v67, v66
	v_add_f32_e32 v56, v57, v56
	v_add_f32_e32 v56, v66, v56
	ds_bpermute_b32 v57, v154, v56
	s_mov_b64 s[8:9], 0x40000
	s_waitcnt lgkmcnt(0)
	v_lshl_add_u64 v[64:65], v[142:143], 0, s[8:9]
	v_cvt_pk_bf16_f32 v63, v58, v59
	s_mov_b64 s[8:9], 0x40100
	global_store_dwordx4 v[64:65], v[60:63], off sc0 sc1
	s_nop 1
	v_cvt_pk_bf16_f32 v52, v52, v53
	v_cvt_pk_bf16_f32 v53, v54, v55
	v_cvt_pk_bf16_f32 v54, v48, v49
	v_add_f32_e32 v48, v56, v57
	ds_bpermute_b32 v49, v155, v48
	v_cvt_pk_bf16_f32 v55, v50, v51
	v_lshl_add_u64 v[50:51], v[142:143], 0, s[8:9]
	global_store_dwordx4 v[50:51], v[52:55], off sc0 sc1
	s_nop 1
	s_and_saveexec_b64 s[8:9], s[0:1]
	s_cbranch_execz .LBB0_2314
	s_mul_i32 s18, s13, 0x43000
	s_ashr_i32 s19, s18, 31
	s_waitcnt lgkmcnt(0)
	v_add_f32_e32 v50, v48, v49
	v_lshl_add_u64 v[48:49], s[18:19], 0, v[112:113]
	s_mul_i32 s14, s48, 0x10c00
	v_lshl_add_u64 v[48:49], v[48:49], 0, s[14:15]
	s_mov_b64 s[18:19], 0x200
	v_lshl_add_u64 v[48:49], v[48:49], 0, s[18:19]
	global_store_dword v[48:49], v50, off sc0 sc1
	s_nop 1
.LBB0_2314:
	s_or_b64 exec, exec, s[8:9]
	v_mul_f32_e32 v50, v45, v45
	v_mul_f32_e32 v51, v47, v47
	v_fmac_f32_e32 v50, v44, v44
	v_fmac_f32_e32 v51, v46, v46
	v_add_f32_e32 v50, v50, v51
	v_mul_f32_e32 v51, v41, v41
	v_fmac_f32_e32 v51, v40, v40
	v_cvt_pk_bf16_f32 v44, v44, v45
	v_cvt_pk_bf16_f32 v45, v46, v47
	v_cvt_pk_bf16_f32 v46, v40, v41
	v_mul_f32_e32 v40, v37, v37
	v_mul_f32_e32 v41, v39, v39
	v_fmac_f32_e32 v40, v36, v36
	v_fmac_f32_e32 v41, v38, v38
	v_add_f32_e32 v40, v40, v41
	v_mul_f32_e32 v41, v33, v33
	v_fmac_f32_e32 v41, v32, v32
	v_add_f32_e32 v50, v50, v51
	v_mul_f32_e32 v51, v43, v43
	v_add_f32_e32 v40, v40, v41
	v_mul_f32_e32 v41, v35, v35
	v_fmac_f32_e32 v51, v42, v42
	v_fmac_f32_e32 v41, v34, v34
	v_add_f32_e32 v50, v51, v50
	v_add_f32_e32 v40, v41, v40
	v_add_f32_e32 v40, v50, v40
	ds_bpermute_b32 v41, v154, v40
	s_mov_b64 s[8:9], 0x48000
	s_waitcnt lgkmcnt(0)
	v_lshl_add_u64 v[48:49], v[142:143], 0, s[8:9]
	v_cvt_pk_bf16_f32 v47, v42, v43
	s_mov_b64 s[8:9], 0x48100
	global_store_dwordx4 v[48:49], v[44:47], off sc0 sc1
	s_nop 1
	v_cvt_pk_bf16_f32 v36, v36, v37
	v_cvt_pk_bf16_f32 v37, v38, v39
	v_cvt_pk_bf16_f32 v38, v32, v33
	v_add_f32_e32 v32, v40, v41
	ds_bpermute_b32 v33, v155, v32
	v_cvt_pk_bf16_f32 v39, v34, v35
	v_lshl_add_u64 v[34:35], v[142:143], 0, s[8:9]
	global_store_dwordx4 v[34:35], v[36:39], off sc0 sc1
	s_nop 1
	s_and_saveexec_b64 s[8:9], s[0:1]
	s_cbranch_execz .LBB0_2316
	s_mul_i32 s18, s13, 0x43000
	s_ashr_i32 s19, s18, 31
	s_waitcnt lgkmcnt(0)
	v_add_f32_e32 v34, v32, v33
	v_lshl_add_u64 v[32:33], s[18:19], 0, v[112:113]
	s_mul_i32 s14, s48, 0x10c00
	v_lshl_add_u64 v[32:33], v[32:33], 0, s[14:15]
	s_mov_b64 s[18:19], 0x240
	v_lshl_add_u64 v[32:33], v[32:33], 0, s[18:19]
	global_store_dword v[32:33], v34, off sc0 sc1
	s_nop 1
.LBB0_2316:
	s_or_b64 exec, exec, s[8:9]
	v_mul_f32_e32 v34, v29, v29
	v_mul_f32_e32 v35, v31, v31
	v_fmac_f32_e32 v34, v28, v28
	v_fmac_f32_e32 v35, v30, v30
	v_add_f32_e32 v34, v34, v35
	v_mul_f32_e32 v35, v25, v25
	v_fmac_f32_e32 v35, v24, v24
	v_cvt_pk_bf16_f32 v28, v28, v29
	v_cvt_pk_bf16_f32 v29, v30, v31
	v_cvt_pk_bf16_f32 v30, v24, v25
	v_mul_f32_e32 v24, v21, v21
	v_mul_f32_e32 v25, v23, v23
	v_fmac_f32_e32 v24, v20, v20
	v_fmac_f32_e32 v25, v22, v22
	v_add_f32_e32 v24, v24, v25
	v_mul_f32_e32 v25, v17, v17
	v_fmac_f32_e32 v25, v16, v16
	v_add_f32_e32 v34, v34, v35
	v_mul_f32_e32 v35, v27, v27
	v_add_f32_e32 v24, v24, v25
	v_mul_f32_e32 v25, v19, v19
	v_fmac_f32_e32 v35, v26, v26
	v_fmac_f32_e32 v25, v18, v18
	v_add_f32_e32 v34, v35, v34
	v_add_f32_e32 v24, v25, v24
	v_add_f32_e32 v24, v34, v24
	ds_bpermute_b32 v25, v154, v24
	s_mov_b64 s[8:9], 0x50000
	s_waitcnt lgkmcnt(0)
	v_lshl_add_u64 v[32:33], v[142:143], 0, s[8:9]
	v_cvt_pk_bf16_f32 v31, v26, v27
	s_mov_b64 s[8:9], 0x50100
	global_store_dwordx4 v[32:33], v[28:31], off sc0 sc1
	s_nop 1
	v_cvt_pk_bf16_f32 v20, v20, v21
	v_cvt_pk_bf16_f32 v21, v22, v23
	v_cvt_pk_bf16_f32 v22, v16, v17
	v_add_f32_e32 v16, v24, v25
	ds_bpermute_b32 v17, v155, v16
	v_cvt_pk_bf16_f32 v23, v18, v19
	v_lshl_add_u64 v[18:19], v[142:143], 0, s[8:9]
	global_store_dwordx4 v[18:19], v[20:23], off sc0 sc1
	s_nop 1
	s_and_saveexec_b64 s[8:9], s[0:1]
	s_cbranch_execz .LBB0_2318
	s_mul_i32 s18, s13, 0x43000
	s_ashr_i32 s19, s18, 31
	s_waitcnt lgkmcnt(0)
	v_add_f32_e32 v18, v16, v17
	v_lshl_add_u64 v[16:17], s[18:19], 0, v[112:113]
	s_mul_i32 s14, s48, 0x10c00
	v_lshl_add_u64 v[16:17], v[16:17], 0, s[14:15]
	s_mov_b64 s[18:19], 0x280
	v_lshl_add_u64 v[16:17], v[16:17], 0, s[18:19]
	global_store_dword v[16:17], v18, off sc0 sc1
	s_nop 1
.LBB0_2318:
	s_or_b64 exec, exec, s[8:9]
	v_mul_f32_e32 v18, v13, v13
	v_mul_f32_e32 v19, v15, v15
	v_fmac_f32_e32 v18, v12, v12
	v_fmac_f32_e32 v19, v14, v14
	v_add_f32_e32 v18, v18, v19
	v_mul_f32_e32 v19, v9, v9
	v_fmac_f32_e32 v19, v8, v8
	v_cvt_pk_bf16_f32 v12, v12, v13
	v_cvt_pk_bf16_f32 v13, v14, v15
	v_cvt_pk_bf16_f32 v14, v8, v9
	v_mul_f32_e32 v8, v5, v5
	v_mul_f32_e32 v9, v7, v7
	v_fmac_f32_e32 v8, v4, v4
	v_fmac_f32_e32 v9, v6, v6
	v_add_f32_e32 v8, v8, v9
	v_mul_f32_e32 v9, v1, v1
	v_fmac_f32_e32 v9, v0, v0
	v_add_f32_e32 v18, v18, v19
	v_mul_f32_e32 v19, v11, v11
	v_add_f32_e32 v8, v8, v9
	v_mul_f32_e32 v9, v3, v3
	v_fmac_f32_e32 v19, v10, v10
	v_fmac_f32_e32 v9, v2, v2
	v_add_f32_e32 v18, v19, v18
	v_add_f32_e32 v8, v9, v8
	v_add_f32_e32 v8, v18, v8
	ds_bpermute_b32 v9, v154, v8
	s_waitcnt lgkmcnt(0)
	v_lshl_add_u64 v[16:17], v[142:143], 0, s[50:51]
	v_cvt_pk_bf16_f32 v15, v10, v11
	s_nop 0
	global_store_dwordx4 v[16:17], v[12:15], off sc0 sc1
	s_nop 1
	v_cvt_pk_bf16_f32 v4, v4, v5
	v_cvt_pk_bf16_f32 v5, v6, v7
	v_cvt_pk_bf16_f32 v6, v0, v1
	v_add_f32_e32 v0, v8, v9
	ds_bpermute_b32 v1, v155, v0
	v_cvt_pk_bf16_f32 v7, v2, v3
	v_lshl_add_u64 v[2:3], v[142:143], 0, s[52:53]
	global_store_dwordx4 v[2:3], v[4:7], off sc0 sc1
	s_nop 1
	s_and_saveexec_b64 s[8:9], s[0:1]
	s_cbranch_execz .LBB0_2320
	s_mul_i32 s18, s13, 0x43000
	s_ashr_i32 s19, s18, 31
	s_waitcnt lgkmcnt(0)
	v_add_f32_e32 v2, v0, v1
	v_lshl_add_u64 v[0:1], s[18:19], 0, v[112:113]
	s_mul_i32 s14, s48, 0x10c00
	v_lshl_add_u64 v[0:1], v[0:1], 0, s[14:15]
	v_lshl_add_u64 v[0:1], v[0:1], 0, s[54:55]
	global_store_dword v[0:1], v2, off sc0 sc1
	s_nop 1

.LBB0_2391:
	v_readlane_b32 s48, v254, 4
	v_readlane_b32 s50, v254, 6
	v_ashrrev_i32_e32 v153, 31, v152
	v_readlane_b32 s51, v254, 7
	s_mov_b64 s[0:1], 0x1000
	v_readlane_b32 s55, v254, 11
	s_waitcnt lgkmcnt(0)
	v_lshl_add_u64 v[0:1], v[152:153], 4, s[50:51]
	v_lshl_add_u64 v[16:17], v[0:1], 0, s[0:1]
	v_add_co_u32_e32 v18, vcc, 0x1000, v0
	s_add_u32 s6, s24, 0x74600
	s_nop 0
	v_addc_co_u32_e32 v19, vcc, 0, v1, vcc
	global_load_dwordx4 v[0:3], v[16:17], off offset:1024
	global_load_dwordx4 v[4:7], v[16:17], off offset:2048
	global_load_dwordx4 v[8:11], v[18:19], off
	global_load_dwordx4 v[12:15], v[16:17], off offset:3072
	v_readlane_b32 s4, v254, 60
	v_readlane_b32 s54, v254, 10
	v_readlane_b32 s56, v254, 12
	v_readlane_b32 s57, v254, 13
	v_readlane_b32 s58, v254, 14
	v_readlane_b32 s59, v254, 15
	v_readlane_b32 s60, v254, 16
	v_readlane_b32 s61, v254, 17
	v_readlane_b32 s62, v254, 18
	v_readlane_b32 s63, v254, 19
	s_addc_u32 s7, s25, 0
	v_readlane_b32 s5, v254, 61
	v_lshlrev_b64 v[20:21], 3, v[152:153]
	s_add_i32 s55, 0, 0x20080
	s_mov_b32 s3, 0
	v_cmp_gt_i32_e64 s[0:1], 16, v152
	v_mul_u32_u24_e32 v16, 0x10c00, v152
	v_mov_b32_e32 v17, 0
	v_lshl_add_u64 v[16:17], v[16:17], 0, s[4:5]
	v_lshl_add_u64 v[18:19], s[20:21], 0, v[20:21]
	v_lshl_add_u64 v[20:21], s[24:25], 0, v[20:21]
	v_mov_b32_e32 v23, 0
	s_movk_i32 s33, 0x214
	s_movk_i32 s54, 0x200
	s_mov_b32 s56, 0xda00000
	s_mov_b32 s57, 0xdb80000
	s_mov_b32 s58, 0xdd00000
	s_mov_b32 s59, 0xde80000
	s_mov_b32 s60, 0xe000000
	s_mov_b32 s61, 0xe180000
	s_mov_b32 s62, 0xe300000
	s_mov_b32 s63, 0xe480000
	s_mov_b32 s64, 0xe600000
	s_mov_b32 s65, 0xe780000
	s_mov_b32 s66, 0xe900000
	v_mov_b32_e32 v122, 0x358637bd
	s_mov_b32 s67, 0x800000
	v_mov_b32_e32 v123, 0x160
	v_mov_b32_e32 v124, s55
	v_readlane_b32 s49, v254, 5
	v_readlane_b32 s52, v254, 8
	v_readlane_b32 s53, v254, 9
	s_branch .LBB0_2395

.LBB0_2477:
	s_mov_b32 s9, s3
	v_mov_b32_e32 v22, 0
	s_and_saveexec_b64 s[24:25], s[0:1]
	s_cbranch_execz .LBB0_2479
	s_lshl_b64 s[18:19], s[8:9], 2
	v_lshl_add_u64 v[24:25], v[16:17], 0, s[18:19]
	global_load_dword v22, v[24:25], off

.LBB0_2493:
	v_mov_b32_e32 v22, 0
	s_and_saveexec_b64 s[24:25], s[0:1]
	s_cbranch_execz .LBB0_2495
	s_lshl_b64 s[18:19], s[2:3], 2
	v_lshl_add_u64 v[24:25], v[16:17], 0, s[18:19]
	global_load_dword v22, v[24:25], off

.LBB0_2525:
	v_mov_b32_e32 v22, 0
	s_and_saveexec_b64 s[16:17], s[0:1]
	s_cbranch_execz .LBB0_2392
	s_lshl_b64 s[18:19], s[2:3], 2
	v_lshl_add_u64 v[24:25], v[16:17], 0, s[18:19]
	global_load_dword v22, v[24:25], off
	s_branch .LBB0_2392
